# stack (v014) + end-of-MMA barrier issued one MFMA pair early with the trailing pair at s_setprio 2 in all six GEMM K-loops
# speedup vs baseline: 1.0042x; 1.0010x over previous
; #define PG8_STAGE(bufoff, gbase, voff) do { _Pragma("unroll") for (int _i = 0; _i < 2; ++_i) \
;         __builtin_amdgcn_global_load_lds((const unsigned*)((const char*)(gbase) + (voff)[_i]), (PG8_LAS unsigned*)(lds + (bufoff) + ldsw + _i * 8192), 16, 0, 0); } while (0)
; #define PG8_LDA(dst, b, h) do { _Pragma("unroll") for (int m = 0; m < 4; ++m) _Pragma("unroll") for (int k = 0; k < 2; ++k) dst[m][k] = *(const PG8_LAS bf16x8*)(lds + PG8_SA(b, h) + aoff + m * 2048 + k * 1024); } while (0)
; #define PG8_LDB(dst, b, h) do { _Pragma("unroll") for (int n = 0; n < 2; ++n) _Pragma("unroll") for (int k = 0; k < 2; ++k) dst[n][k] = *(const PG8_LAS bf16x8*)(lds + PG8_SB(b, h) + boff + n * 2048 + k * 1024); } while (0)
; #define PG8_WAIT_V(n) asm volatile("s_waitcnt vmcnt(" #n ")" ::: "memory")
; #define PG8_WAIT_L(n) asm volatile("s_waitcnt lgkmcnt(" #n ")" ::: "memory")
; #define PG8_BAR __builtin_amdgcn_s_barrier()
; #define PG8_SCHED __builtin_amdgcn_sched_barrier(0)
; template <class Epi, class Sched, bool ALIGN_EPI = false, bool SP2 = false>
; __device__ __forceinline__ void gemm_phase(PG8_LAS unsigned char* lds, const Gemm g, const Sched& S, const Epi& E, int tid_in) {
;     ...
;         const bool has_next = S.next(ui + 1, nxt);
;         const char* nA = has_next ? (const char*)g.A + (size_t)nxt.pm * tstep : cA; const char* nB = has_next ? (const char*)g.Bt + (size_t)nxt.pn * tstep : cB;
;         for (int t = 0; t < nt; t += 2) {
;             const bool last = (t == nt - 2);
;             const char* a1 = cA + (size_t)(t + 1) * kstep;
;             const char* a2 = last ? nA : cA + (size_t)(t + 2) * kstep; const char* b2 = last ? nB : cB + (size_t)(t + 2) * kstep;
;             const char* a3 = a2 + kstep; const char* b3 = b2 + kstep;
;             if (last && has_next) S.a_ready(nxt);
;             if constexpr (SP2) {
;             PG8_LDB(B0, 0, 0); PG8_LDB(B1, 0, 1); PG8_SCHED; PG8_LDA(At, 0, 0); PG8_STAGE(PG8_SA(1, 1), a1 + hstepA, voffA);
;             PG8_WAIT_V(8); PG8_WAIT_L(0); PG8_BAR; PG8_MMA(0, 0, At, B0); PG8_MMA(0, 1, At, B1); PG8_BAR; PG8_SCHED;
;             PG8_LDA(At, 0, 1); PG8_STAGE(PG8_SB(0, 0), b2, voffB); PG8_STAGE(PG8_SB(0, 1), b2 + hstep, voffB); PG8_STAGE(PG8_SA(0, 0), a2, voffA);
;             PG8_WAIT_V(8); PG8_WAIT_L(0); PG8_BAR; PG8_MMA(1, 0, At, B0); PG8_MMA(1, 1, At, B1); PG8_BAR; PG8_SCHED;
.LBB0_158:
	ds_read_b128 v[112:115], v200
	ds_read_b128 v[116:119], v200 offset:1024
	ds_read_b128 v[136:139], v200 offset:2048
	ds_read_b128 v[140:143], v200 offset:3072
	ds_read_b128 v[172:175], v201
	ds_read_b128 v[176:179], v201 offset:1024
	ds_read_b128 v[180:183], v201 offset:2048
	ds_read_b128 v[184:187], v201 offset:3072
	s_add_u32 s42, s4, 0x100
	s_addc_u32 s43, s5, 0
	s_cmp_eq_u32 s48, 60
	s_cselect_b32 s47, s1, s43
	s_cselect_b32 s46, s19, s42
	s_cselect_b32 s45, s31, s41
	s_cselect_b32 s44, s33, s35
	s_add_i32 m0, s71, 0xc000
	ds_read_b128 v[188:191], v202
	ds_read_b128 v[192:195], v202 offset:1024
	ds_read_b128 v[208:211], v202 offset:2048
	ds_read_b128 v[212:215], v202 offset:3072
	ds_read_b128 v[216:219], v202 offset:4096
	ds_read_b128 v[220:223], v202 offset:5120
	ds_read_b128 v[224:227], v202 offset:6144
	ds_read_b128 v[228:231], v202 offset:7168
	global_load_lds_dwordx4 v160, s[4:5]
	s_add_i32 m0, s71, 0xe000
	s_nop 0
	global_load_lds_dwordx4 v162, s[4:5]
	s_waitcnt vmcnt(8)
	s_waitcnt lgkmcnt(0)
	s_barrier
	s_setprio 1
	s_waitcnt lgkmcnt(0)
	v_mfma_f32_16x16x32_bf16 v[132:135], v[112:115], v[188:191], v[132:135]
	v_mfma_f32_16x16x32_bf16 v[132:135], v[116:119], v[192:195], v[132:135]
	v_mfma_f32_16x16x32_bf16 v[128:131], v[140:143], v[192:195], v[128:131]
	v_mfma_f32_16x16x32_bf16 v[128:131], v[136:139], v[188:191], v[128:131]
	v_mfma_f32_16x16x32_bf16 v[120:123], v[136:139], v[208:211], v[120:123]
	v_mfma_f32_16x16x32_bf16 v[120:123], v[140:143], v[212:215], v[120:123]
	v_mfma_f32_16x16x32_bf16 v[124:127], v[116:119], v[212:215], v[124:127]
	v_mfma_f32_16x16x32_bf16 v[124:127], v[112:115], v[208:211], v[124:127]
	v_mfma_f32_16x16x32_bf16 v[108:111], v[112:115], v[216:219], v[108:111]
	v_mfma_f32_16x16x32_bf16 v[108:111], v[116:119], v[220:223], v[108:111]
	v_mfma_f32_16x16x32_bf16 v[104:107], v[140:143], v[220:223], v[104:107]
	v_mfma_f32_16x16x32_bf16 v[104:107], v[136:139], v[216:219], v[104:107]
	v_mfma_f32_16x16x32_bf16 v[96:99], v[136:139], v[224:227], v[96:99]
	v_mfma_f32_16x16x32_bf16 v[96:99], v[140:143], v[228:231], v[96:99]
	v_mfma_f32_16x16x32_bf16 v[100:103], v[116:119], v[228:231], v[100:103]
	v_mfma_f32_16x16x32_bf16 v[100:103], v[112:115], v[224:227], v[100:103]
	s_setprio 0
	s_setprio 1
	v_mfma_f32_16x16x32_bf16 v[60:63], v[172:175], v[188:191], v[60:63]
	v_mfma_f32_16x16x32_bf16 v[60:63], v[176:179], v[192:195], v[60:63]
	v_mfma_f32_16x16x32_bf16 v[56:59], v[184:187], v[192:195], v[56:59]
	v_mfma_f32_16x16x32_bf16 v[56:59], v[180:183], v[188:191], v[56:59]
	v_mfma_f32_16x16x32_bf16 v[48:51], v[180:183], v[208:211], v[48:51]
	v_mfma_f32_16x16x32_bf16 v[48:51], v[184:187], v[212:215], v[48:51]
	v_mfma_f32_16x16x32_bf16 v[52:55], v[176:179], v[212:215], v[52:55]
	v_mfma_f32_16x16x32_bf16 v[52:55], v[172:175], v[208:211], v[52:55]
	v_mfma_f32_16x16x32_bf16 v[44:47], v[172:175], v[216:219], v[44:47]
	v_mfma_f32_16x16x32_bf16 v[44:47], v[176:179], v[220:223], v[44:47]
	v_mfma_f32_16x16x32_bf16 v[40:43], v[184:187], v[220:223], v[40:43]
	v_mfma_f32_16x16x32_bf16 v[40:43], v[180:183], v[216:219], v[40:43]
	v_mfma_f32_16x16x32_bf16 v[32:35], v[180:183], v[224:227], v[32:35]
	v_mfma_f32_16x16x32_bf16 v[32:35], v[184:187], v[228:231], v[32:35]
	s_setprio 2
	s_barrier
	v_mfma_f32_16x16x32_bf16 v[36:39], v[176:179], v[228:231], v[36:39]
	v_mfma_f32_16x16x32_bf16 v[36:39], v[172:175], v[224:227], v[36:39]
	s_setprio 0
	s_add_u32 s98, s44, 0x80
	s_addc_u32 s99, s45, 0
	s_add_u32 s100, s46, 0x80
	s_addc_u32 s101, s47, 0
	s_add_i32 s4, s91, s70
	s_mov_b32 m0, s4
	ds_read_b128 v[188:191], v202 offset:16384
	ds_read_b128 v[192:195], v202 offset:17408
	ds_read_b128 v[208:211], v202 offset:18432
	ds_read_b128 v[212:215], v202 offset:19456
	ds_read_b128 v[216:219], v202 offset:20480
	ds_read_b128 v[220:223], v202 offset:21504
	ds_read_b128 v[224:227], v202 offset:22528
	ds_read_b128 v[228:231], v202 offset:23552
	global_load_lds_dwordx4 v146, s[44:45]
	s_add_i32 m0, s4, 0x2000
	s_add_u32 s4, s44, 0x100000
	s_addc_u32 s5, s45, 0
	s_add_i32 s49, s92, s70
	global_load_lds_dwordx4 v150, s[44:45]
	s_mov_b32 m0, s49
	s_nop 0
	global_load_lds_dwordx4 v146, s[4:5]
	s_add_i32 m0, s49, 0x2000
	s_nop 0
	global_load_lds_dwordx4 v150, s[4:5]
	s_mov_b32 m0, s71
	s_nop 0
	global_load_lds_dwordx4 v144, s[46:47]
	s_mov_b32 m0, s72
	s_nop 0
	global_load_lds_dwordx4 v148, s[46:47]
	s_waitcnt vmcnt(8)
	s_waitcnt lgkmcnt(0)
	s_barrier
	s_setprio 1
	s_waitcnt lgkmcnt(0)
	v_mfma_f32_16x16x32_bf16 v[92:95], v[112:115], v[188:191], v[92:95]
	v_mfma_f32_16x16x32_bf16 v[92:95], v[116:119], v[192:195], v[92:95]
	v_mfma_f32_16x16x32_bf16 v[88:91], v[140:143], v[192:195], v[88:91]
	v_mfma_f32_16x16x32_bf16 v[88:91], v[136:139], v[188:191], v[88:91]
	v_mfma_f32_16x16x32_bf16 v[80:83], v[136:139], v[208:211], v[80:83]
	v_mfma_f32_16x16x32_bf16 v[80:83], v[140:143], v[212:215], v[80:83]
	v_mfma_f32_16x16x32_bf16 v[84:87], v[116:119], v[212:215], v[84:87]
	v_mfma_f32_16x16x32_bf16 v[84:87], v[112:115], v[208:211], v[84:87]
	v_mfma_f32_16x16x32_bf16 v[76:79], v[112:115], v[216:219], v[76:79]
	v_mfma_f32_16x16x32_bf16 v[76:79], v[116:119], v[220:223], v[76:79]
	v_mfma_f32_16x16x32_bf16 v[72:75], v[140:143], v[220:223], v[72:75]
	v_mfma_f32_16x16x32_bf16 v[72:75], v[136:139], v[216:219], v[72:75]
	v_mfma_f32_16x16x32_bf16 v[64:67], v[136:139], v[224:227], v[64:67]
	v_mfma_f32_16x16x32_bf16 v[64:67], v[140:143], v[228:231], v[64:67]
	v_mfma_f32_16x16x32_bf16 v[68:71], v[116:119], v[228:231], v[68:71]
	v_mfma_f32_16x16x32_bf16 v[68:71], v[112:115], v[224:227], v[68:71]
	s_setprio 0
	s_setprio 1
	v_mfma_f32_16x16x32_bf16 v[28:31], v[172:175], v[188:191], v[28:31]
	v_mfma_f32_16x16x32_bf16 v[28:31], v[176:179], v[192:195], v[28:31]
	v_mfma_f32_16x16x32_bf16 v[24:27], v[184:187], v[192:195], v[24:27]
	v_mfma_f32_16x16x32_bf16 v[24:27], v[180:183], v[188:191], v[24:27]
	v_mfma_f32_16x16x32_bf16 v[16:19], v[180:183], v[208:211], v[16:19]
	v_mfma_f32_16x16x32_bf16 v[16:19], v[184:187], v[212:215], v[16:19]
	v_mfma_f32_16x16x32_bf16 v[20:23], v[176:179], v[212:215], v[20:23]
	v_mfma_f32_16x16x32_bf16 v[20:23], v[172:175], v[208:211], v[20:23]
	v_mfma_f32_16x16x32_bf16 v[12:15], v[172:175], v[216:219], v[12:15]
	v_mfma_f32_16x16x32_bf16 v[12:15], v[176:179], v[220:223], v[12:15]
	v_mfma_f32_16x16x32_bf16 v[8:11], v[184:187], v[220:223], v[8:11]
	v_mfma_f32_16x16x32_bf16 v[8:11], v[180:183], v[216:219], v[8:11]
	v_mfma_f32_16x16x32_bf16 v[0:3], v[180:183], v[224:227], v[0:3]
	v_mfma_f32_16x16x32_bf16 v[0:3], v[184:187], v[228:231], v[0:3]
	s_setprio 2
	s_barrier
; #define PG8_STAGE(bufoff, gbase, voff) do { _Pragma("unroll") for (int _i = 0; _i < 2; ++_i) \
;         __builtin_amdgcn_global_load_lds((const unsigned*)((const char*)(gbase) + (voff)[_i]), (PG8_LAS unsigned*)(lds + (bufoff) + ldsw + _i * 8192), 16, 0, 0); } while (0)
; #define PG8_LDA(dst, b, h) do { _Pragma("unroll") for (int m = 0; m < 4; ++m) _Pragma("unroll") for (int k = 0; k < 2; ++k) dst[m][k] = *(const PG8_LAS bf16x8*)(lds + PG8_SA(b, h) + aoff + m * 2048 + k * 1024); } while (0)
; #define PG8_LDB(dst, b, h) do { _Pragma("unroll") for (int n = 0; n < 2; ++n) _Pragma("unroll") for (int k = 0; k < 2; ++k) dst[n][k] = *(const PG8_LAS bf16x8*)(lds + PG8_SB(b, h) + boff + n * 2048 + k * 1024); } while (0)
; #define PG8_WAIT_V(n) asm volatile("s_waitcnt vmcnt(" #n ")" ::: "memory")
; #define PG8_WAIT_L(n) asm volatile("s_waitcnt lgkmcnt(" #n ")" ::: "memory")
; #define PG8_BAR __builtin_amdgcn_s_barrier()
; #define PG8_SCHED __builtin_amdgcn_sched_barrier(0)
; template <class Epi, class Sched, bool ALIGN_EPI = false, bool SP2 = false>
; __device__ __forceinline__ void gemm_phase(PG8_LAS unsigned char* lds, const Gemm g, const Sched& S, const Epi& E, int tid_in) {
;     ...
;             PG8_WAIT_V(8); PG8_WAIT_L(0); PG8_BAR; PG8_MMA(1, 0, At, B0); PG8_MMA(1, 1, At, B1); PG8_BAR; PG8_SCHED;
;             PG8_LDB(B0, 1, 0); PG8_LDB(B1, 1, 1); PG8_SCHED; PG8_LDA(At, 1, 0); PG8_STAGE(PG8_SA(0, 1), a2 + hstepA, voffA);
;             PG8_WAIT_V(8); PG8_WAIT_L(0); PG8_BAR; PG8_MMA(0, 0, At, B0); PG8_MMA(0, 1, At, B1); PG8_BAR; PG8_SCHED;
;             PG8_LDA(At, 1, 1); PG8_STAGE(PG8_SB(1, 0), b3, voffB); PG8_STAGE(PG8_SB(1, 1), b3 + hstep, voffB); PG8_STAGE(PG8_SA(1, 0), a3, voffA);
;             PG8_WAIT_V(8); PG8_WAIT_L(0); PG8_BAR; PG8_MMA(1, 0, At, B0); PG8_MMA(1, 1, At, B1); PG8_BAR; PG8_SCHED;
	v_mfma_f32_16x16x32_bf16 v[4:7], v[176:179], v[228:231], v[4:7]
	v_mfma_f32_16x16x32_bf16 v[4:7], v[172:175], v[224:227], v[4:7]
	s_setprio 0
	s_add_i32 s49, 0, 0x18000
	s_add_i32 s50, 0, 0x1c000
	v_add_u32_e32 v140, s49, v197
	v_add_u32_e32 v152, s50, v197
	ds_read_b128 v[112:115], v140
	ds_read_b128 v[116:119], v140 offset:1024
	ds_read_b128 v[136:139], v140 offset:2048
	ds_read_b128 v[140:143], v140 offset:3072
	ds_read_b128 v[172:175], v152
	ds_read_b128 v[176:179], v152 offset:1024
	ds_read_b128 v[180:183], v152 offset:2048
	ds_read_b128 v[184:187], v152 offset:3072
	s_add_u32 s4, s46, 0x8000
	s_addc_u32 s5, s47, 0
	s_mov_b32 m0, s73
	ds_read_b128 v[188:191], v202 offset:32768
	ds_read_b128 v[192:195], v202 offset:33792
	ds_read_b128 v[208:211], v202 offset:34816
	ds_read_b128 v[212:215], v202 offset:35840
	ds_read_b128 v[216:219], v202 offset:36864
	ds_read_b128 v[220:223], v202 offset:37888
	ds_read_b128 v[224:227], v202 offset:38912
	ds_read_b128 v[228:231], v202 offset:39936
	global_load_lds_dwordx4 v144, s[4:5]
	s_mov_b32 m0, s74
	s_nop 0
	global_load_lds_dwordx4 v148, s[4:5]
	s_waitcnt vmcnt(8)
	s_waitcnt lgkmcnt(0)
	s_barrier
	s_setprio 1
	s_waitcnt lgkmcnt(0)
	v_mfma_f32_16x16x32_bf16 v[132:135], v[112:115], v[188:191], v[132:135]
	v_mfma_f32_16x16x32_bf16 v[132:135], v[116:119], v[192:195], v[132:135]
	v_mfma_f32_16x16x32_bf16 v[128:131], v[140:143], v[192:195], v[128:131]
	v_mfma_f32_16x16x32_bf16 v[128:131], v[136:139], v[188:191], v[128:131]
	v_mfma_f32_16x16x32_bf16 v[120:123], v[136:139], v[208:211], v[120:123]
	v_mfma_f32_16x16x32_bf16 v[120:123], v[140:143], v[212:215], v[120:123]
	v_mfma_f32_16x16x32_bf16 v[124:127], v[116:119], v[212:215], v[124:127]
	v_mfma_f32_16x16x32_bf16 v[124:127], v[112:115], v[208:211], v[124:127]
	v_mfma_f32_16x16x32_bf16 v[108:111], v[112:115], v[216:219], v[108:111]
	v_mfma_f32_16x16x32_bf16 v[108:111], v[116:119], v[220:223], v[108:111]
	v_mfma_f32_16x16x32_bf16 v[104:107], v[140:143], v[220:223], v[104:107]
	v_mfma_f32_16x16x32_bf16 v[104:107], v[136:139], v[216:219], v[104:107]
	v_mfma_f32_16x16x32_bf16 v[96:99], v[136:139], v[224:227], v[96:99]
	v_mfma_f32_16x16x32_bf16 v[96:99], v[140:143], v[228:231], v[96:99]
	v_mfma_f32_16x16x32_bf16 v[100:103], v[116:119], v[228:231], v[100:103]
	v_mfma_f32_16x16x32_bf16 v[100:103], v[112:115], v[224:227], v[100:103]
	s_setprio 0
	s_setprio 1
	v_mfma_f32_16x16x32_bf16 v[60:63], v[172:175], v[188:191], v[60:63]
	v_mfma_f32_16x16x32_bf16 v[60:63], v[176:179], v[192:195], v[60:63]
	v_mfma_f32_16x16x32_bf16 v[56:59], v[184:187], v[192:195], v[56:59]
	v_mfma_f32_16x16x32_bf16 v[56:59], v[180:183], v[188:191], v[56:59]
	v_mfma_f32_16x16x32_bf16 v[48:51], v[180:183], v[208:211], v[48:51]
	v_mfma_f32_16x16x32_bf16 v[48:51], v[184:187], v[212:215], v[48:51]
	v_mfma_f32_16x16x32_bf16 v[52:55], v[176:179], v[212:215], v[52:55]
	v_mfma_f32_16x16x32_bf16 v[52:55], v[172:175], v[208:211], v[52:55]
	v_mfma_f32_16x16x32_bf16 v[44:47], v[172:175], v[216:219], v[44:47]
	v_mfma_f32_16x16x32_bf16 v[44:47], v[176:179], v[220:223], v[44:47]
	v_mfma_f32_16x16x32_bf16 v[40:43], v[184:187], v[220:223], v[40:43]
	v_mfma_f32_16x16x32_bf16 v[40:43], v[180:183], v[216:219], v[40:43]
	v_mfma_f32_16x16x32_bf16 v[32:35], v[180:183], v[224:227], v[32:35]
	v_mfma_f32_16x16x32_bf16 v[32:35], v[184:187], v[228:231], v[32:35]
	s_setprio 2
	s_barrier
	v_mfma_f32_16x16x32_bf16 v[36:39], v[176:179], v[228:231], v[36:39]
	v_mfma_f32_16x16x32_bf16 v[36:39], v[172:175], v[224:227], v[36:39]
	s_setprio 0
	s_add_i32 s4, s49, s70
	s_mov_b32 m0, s4
	ds_read_b128 v[188:191], v202 offset:49152
	ds_read_b128 v[192:195], v202 offset:50176
	ds_read_b128 v[208:211], v202 offset:51200
	ds_read_b128 v[212:215], v202 offset:52224
	ds_read_b128 v[216:219], v202 offset:53248
	ds_read_b128 v[220:223], v202 offset:54272
	ds_read_b128 v[224:227], v202 offset:55296
	ds_read_b128 v[228:231], v202 offset:56320
	global_load_lds_dwordx4 v146, s[98:99]
	s_add_i32 m0, s4, 0x2000
	s_add_u32 s4, s44, 0x100080
	s_addc_u32 s5, s45, 0
	s_add_i32 s44, s50, s70
	global_load_lds_dwordx4 v150, s[98:99]
	s_mov_b32 m0, s44
	s_nop 0
	global_load_lds_dwordx4 v146, s[4:5]
	s_add_i32 m0, s44, 0x2000
	s_nop 0
	global_load_lds_dwordx4 v150, s[4:5]
	s_mov_b32 m0, s79
	s_nop 0
	global_load_lds_dwordx4 v144, s[100:101]
	s_mov_b32 m0, s61
	s_nop 0
	global_load_lds_dwordx4 v148, s[100:101]
	s_waitcnt vmcnt(8)
	s_waitcnt lgkmcnt(0)
	s_barrier
	s_setprio 1
	s_waitcnt lgkmcnt(0)
	v_mfma_f32_16x16x32_bf16 v[92:95], v[112:115], v[188:191], v[92:95]
	v_mfma_f32_16x16x32_bf16 v[92:95], v[116:119], v[192:195], v[92:95]
	v_mfma_f32_16x16x32_bf16 v[88:91], v[140:143], v[192:195], v[88:91]
	v_mfma_f32_16x16x32_bf16 v[88:91], v[136:139], v[188:191], v[88:91]
	v_mfma_f32_16x16x32_bf16 v[80:83], v[136:139], v[208:211], v[80:83]
	v_mfma_f32_16x16x32_bf16 v[80:83], v[140:143], v[212:215], v[80:83]
	v_mfma_f32_16x16x32_bf16 v[84:87], v[116:119], v[212:215], v[84:87]
	v_mfma_f32_16x16x32_bf16 v[84:87], v[112:115], v[208:211], v[84:87]
	v_mfma_f32_16x16x32_bf16 v[76:79], v[112:115], v[216:219], v[76:79]
	v_mfma_f32_16x16x32_bf16 v[76:79], v[116:119], v[220:223], v[76:79]
	v_mfma_f32_16x16x32_bf16 v[72:75], v[140:143], v[220:223], v[72:75]
	v_mfma_f32_16x16x32_bf16 v[72:75], v[136:139], v[216:219], v[72:75]
	v_mfma_f32_16x16x32_bf16 v[64:67], v[136:139], v[224:227], v[64:67]
	v_mfma_f32_16x16x32_bf16 v[64:67], v[140:143], v[228:231], v[64:67]
	v_mfma_f32_16x16x32_bf16 v[68:71], v[116:119], v[228:231], v[68:71]
	v_mfma_f32_16x16x32_bf16 v[68:71], v[112:115], v[224:227], v[68:71]
	s_setprio 0
	s_setprio 1
	v_mfma_f32_16x16x32_bf16 v[28:31], v[172:175], v[188:191], v[28:31]
	v_mfma_f32_16x16x32_bf16 v[28:31], v[176:179], v[192:195], v[28:31]
	v_mfma_f32_16x16x32_bf16 v[24:27], v[184:187], v[192:195], v[24:27]
	v_mfma_f32_16x16x32_bf16 v[24:27], v[180:183], v[188:191], v[24:27]
	v_mfma_f32_16x16x32_bf16 v[16:19], v[180:183], v[208:211], v[16:19]
	v_mfma_f32_16x16x32_bf16 v[16:19], v[184:187], v[212:215], v[16:19]
	v_mfma_f32_16x16x32_bf16 v[20:23], v[176:179], v[212:215], v[20:23]
	v_mfma_f32_16x16x32_bf16 v[20:23], v[172:175], v[208:211], v[20:23]
	v_mfma_f32_16x16x32_bf16 v[12:15], v[172:175], v[216:219], v[12:15]
	v_mfma_f32_16x16x32_bf16 v[12:15], v[176:179], v[220:223], v[12:15]
	v_mfma_f32_16x16x32_bf16 v[8:11], v[184:187], v[220:223], v[8:11]
	v_mfma_f32_16x16x32_bf16 v[8:11], v[180:183], v[216:219], v[8:11]
	v_mfma_f32_16x16x32_bf16 v[0:3], v[180:183], v[224:227], v[0:3]
	v_mfma_f32_16x16x32_bf16 v[0:3], v[184:187], v[228:231], v[0:3]
	s_setprio 2
	s_barrier
	v_mfma_f32_16x16x32_bf16 v[4:7], v[176:179], v[228:231], v[4:7]
	v_mfma_f32_16x16x32_bf16 v[4:7], v[172:175], v[224:227], v[4:7]
	s_setprio 0
	s_add_i32 s48, s48, 2
	s_add_u32 s35, s35, 0x100
	s_addc_u32 s41, s41, 0
	s_cmp_gt_u32 s48, 61
	s_mov_b64 s[4:5], s[42:43]
	s_cbranch_scc0 .LBB0_158
	s_and_b64 vcc, exec, s[24:25]
	s_cbranch_vccnz .LBB0_163
	v_lshl_add_u32 v172, s0, 8, v198
	s_cmpk_lg_i32 s40, 0x48
	s_mov_b64 s[4:5], -1
	s_cbranch_scc1 .LBB0_164

; #define PG8_STAGE(bufoff, gbase, voff) do { _Pragma("unroll") for (int _i = 0; _i < 2; ++_i) \
;         __builtin_amdgcn_global_load_lds((const unsigned*)((const char*)(gbase) + (voff)[_i]), (PG8_LAS unsigned*)(lds + (bufoff) + ldsw + _i * 8192), 16, 0, 0); } while (0)
; #define PG8_LDA(dst, b, h) do { _Pragma("unroll") for (int m = 0; m < 4; ++m) _Pragma("unroll") for (int k = 0; k < 2; ++k) dst[m][k] = *(const PG8_LAS bf16x8*)(lds + PG8_SA(b, h) + aoff + m * 2048 + k * 1024); } while (0)
; #define PG8_LDB(dst, b, h) do { _Pragma("unroll") for (int n = 0; n < 2; ++n) _Pragma("unroll") for (int k = 0; k < 2; ++k) dst[n][k] = *(const PG8_LAS bf16x8*)(lds + PG8_SB(b, h) + boff + n * 2048 + k * 1024); } while (0)
; #define PG8_WAIT_V(n) asm volatile("s_waitcnt vmcnt(" #n ")" ::: "memory")
; #define PG8_WAIT_L(n) asm volatile("s_waitcnt lgkmcnt(" #n ")" ::: "memory")
; #define PG8_BAR __builtin_amdgcn_s_barrier()
; #define PG8_SCHED __builtin_amdgcn_sched_barrier(0)
; template <class Epi, class Sched, bool ALIGN_EPI = false, bool SP2 = false>
; __device__ __forceinline__ void gemm_phase(PG8_LAS unsigned char* lds, const Gemm g, const Sched& S, const Epi& E, int tid_in) {
;     ...
;         for (int t = 0; t < nt; t += 2) {
;             const bool last = (t == nt - 2);
;             const char* a1 = cA + (size_t)(t + 1) * kstep;
;             const char* a2 = last ? nA : cA + (size_t)(t + 2) * kstep; const char* b2 = last ? nB : cB + (size_t)(t + 2) * kstep;
;             const char* a3 = a2 + kstep; const char* b3 = b2 + kstep;
;             if (last && has_next) S.a_ready(nxt);
;             if constexpr (SP2) {
;             PG8_LDB(B0, 0, 0); PG8_LDB(B1, 0, 1); PG8_SCHED; PG8_LDA(At, 0, 0); PG8_STAGE(PG8_SA(1, 1), a1 + hstepA, voffA);
;             PG8_WAIT_V(8); PG8_WAIT_L(0); PG8_BAR; PG8_MMA(0, 0, At, B0); PG8_MMA(0, 1, At, B1); PG8_BAR; PG8_SCHED;
;             PG8_LDA(At, 0, 1); PG8_STAGE(PG8_SB(0, 0), b2, voffB); PG8_STAGE(PG8_SB(0, 1), b2 + hstep, voffB); PG8_STAGE(PG8_SA(0, 0), a2, voffA);
;             PG8_WAIT_V(8); PG8_WAIT_L(0); PG8_BAR; PG8_MMA(1, 0, At, B0); PG8_MMA(1, 1, At, B1); PG8_BAR; PG8_SCHED;
.LBB0_927:
	ds_read_b128 v[144:147], v151
	ds_read_b128 v[154:157], v151 offset:1024
	ds_read_b128 v[158:161], v151 offset:2048
	ds_read_b128 v[162:165], v151 offset:3072
	ds_read_b128 v[166:169], v152
	ds_read_b128 v[170:173], v152 offset:1024
	ds_read_b128 v[174:177], v152 offset:2048
	ds_read_b128 v[178:181], v152 offset:3072
	s_add_u32 s24, s22, 0xffe00080
	s_addc_u32 s25, s23, -1
	s_cmpk_eq_i32 s50, 0x7c
	s_cselect_b32 s27, s15, s25
	s_cselect_b32 s26, s46, s24
	s_cselect_b32 s25, s13, s49
	s_cselect_b32 s24, s47, s48
	s_add_i32 m0, s21, 0xc000
	ds_read_b128 v[182:185], v153
	ds_read_b128 v[186:189], v153 offset:1024
	ds_read_b128 v[190:193], v153 offset:2048
	ds_read_b128 v[194:197], v153 offset:3072
	ds_read_b128 v[198:201], v153 offset:4096
	ds_read_b128 v[202:205], v153 offset:5120
	ds_read_b128 v[206:209], v153 offset:6144
	ds_read_b128 v[210:213], v153 offset:7168
	global_load_lds_dwordx4 v136, s[22:23]
	s_add_i32 m0, s21, 0xe000
	s_nop 0
	global_load_lds_dwordx4 v138, s[22:23]
	s_waitcnt vmcnt(8)
	s_waitcnt lgkmcnt(0)
	s_barrier
	s_setprio 1
	s_waitcnt lgkmcnt(0)
	v_mfma_f32_16x16x32_bf16 v[124:127], v[144:147], v[182:185], v[124:127]
	v_mfma_f32_16x16x32_bf16 v[124:127], v[154:157], v[186:189], v[124:127]
	v_mfma_f32_16x16x32_bf16 v[120:123], v[162:165], v[186:189], v[120:123]
	v_mfma_f32_16x16x32_bf16 v[120:123], v[158:161], v[182:185], v[120:123]
	v_mfma_f32_16x16x32_bf16 v[104:107], v[158:161], v[190:193], v[104:107]
	v_mfma_f32_16x16x32_bf16 v[104:107], v[162:165], v[194:197], v[104:107]
	v_mfma_f32_16x16x32_bf16 v[108:111], v[154:157], v[194:197], v[108:111]
	v_mfma_f32_16x16x32_bf16 v[108:111], v[144:147], v[190:193], v[108:111]
	v_mfma_f32_16x16x32_bf16 v[92:95], v[144:147], v[198:201], v[92:95]
	v_mfma_f32_16x16x32_bf16 v[92:95], v[154:157], v[202:205], v[92:95]
	v_mfma_f32_16x16x32_bf16 v[88:91], v[162:165], v[202:205], v[88:91]
	v_mfma_f32_16x16x32_bf16 v[88:91], v[158:161], v[198:201], v[88:91]
	v_mfma_f32_16x16x32_bf16 v[72:75], v[158:161], v[206:209], v[72:75]
	v_mfma_f32_16x16x32_bf16 v[72:75], v[162:165], v[210:213], v[72:75]
	v_mfma_f32_16x16x32_bf16 v[76:79], v[154:157], v[210:213], v[76:79]
	v_mfma_f32_16x16x32_bf16 v[76:79], v[144:147], v[206:209], v[76:79]
	s_setprio 0
	s_setprio 1
	v_mfma_f32_16x16x32_bf16 v[116:119], v[166:169], v[182:185], v[116:119]
	v_mfma_f32_16x16x32_bf16 v[116:119], v[170:173], v[186:189], v[116:119]
	v_mfma_f32_16x16x32_bf16 v[112:115], v[178:181], v[186:189], v[112:115]
	v_mfma_f32_16x16x32_bf16 v[112:115], v[174:177], v[182:185], v[112:115]
	v_mfma_f32_16x16x32_bf16 v[96:99], v[174:177], v[190:193], v[96:99]
	v_mfma_f32_16x16x32_bf16 v[96:99], v[178:181], v[194:197], v[96:99]
	v_mfma_f32_16x16x32_bf16 v[100:103], v[170:173], v[194:197], v[100:103]
	v_mfma_f32_16x16x32_bf16 v[100:103], v[166:169], v[190:193], v[100:103]
	v_mfma_f32_16x16x32_bf16 v[84:87], v[166:169], v[198:201], v[84:87]
	v_mfma_f32_16x16x32_bf16 v[84:87], v[170:173], v[202:205], v[84:87]
	v_mfma_f32_16x16x32_bf16 v[80:83], v[178:181], v[202:205], v[80:83]
	v_mfma_f32_16x16x32_bf16 v[80:83], v[174:177], v[198:201], v[80:83]
	v_mfma_f32_16x16x32_bf16 v[64:67], v[174:177], v[206:209], v[64:67]
	v_mfma_f32_16x16x32_bf16 v[64:67], v[178:181], v[210:213], v[64:67]
	s_setprio 2
	s_barrier
	v_mfma_f32_16x16x32_bf16 v[68:71], v[170:173], v[210:213], v[68:71]
	v_mfma_f32_16x16x32_bf16 v[68:71], v[166:169], v[206:209], v[68:71]
	s_setprio 0
	s_add_u32 s98, s24, 0x80
	s_addc_u32 s99, s25, 0
	s_add_u32 s100, s26, 0x80
	s_addc_u32 s101, s27, 0
	s_add_i32 s51, s43, s34
	s_mov_b32 m0, s51
	ds_read_b128 v[182:185], v153 offset:16384
	ds_read_b128 v[186:189], v153 offset:17408
	ds_read_b128 v[190:193], v153 offset:18432
	ds_read_b128 v[194:197], v153 offset:19456
	ds_read_b128 v[198:201], v153 offset:20480
	ds_read_b128 v[202:205], v153 offset:21504
	ds_read_b128 v[206:209], v153 offset:22528
	ds_read_b128 v[210:213], v153 offset:23552
	global_load_lds_dwordx4 v130, s[24:25]
	s_add_i32 m0, s51, 0x2000
	s_add_u32 s52, s24, 0x200000
	s_addc_u32 s53, s25, 0
	s_add_i32 s51, s44, s34
	global_load_lds_dwordx4 v134, s[24:25]
	s_mov_b32 m0, s51
	s_nop 0
	global_load_lds_dwordx4 v130, s[52:53]
	s_add_i32 m0, s51, 0x2000
	s_nop 0
	global_load_lds_dwordx4 v134, s[52:53]
	s_mov_b32 m0, s21
	s_nop 0
	global_load_lds_dwordx4 v128, s[26:27]
	s_mov_b32 m0, s35
	s_nop 0
	global_load_lds_dwordx4 v132, s[26:27]
	s_waitcnt vmcnt(8)
	s_waitcnt lgkmcnt(0)
	s_barrier
	s_setprio 1
	s_waitcnt lgkmcnt(0)
	v_mfma_f32_16x16x32_bf16 v[60:63], v[144:147], v[182:185], v[60:63]
	v_mfma_f32_16x16x32_bf16 v[60:63], v[154:157], v[186:189], v[60:63]
	v_mfma_f32_16x16x32_bf16 v[56:59], v[162:165], v[186:189], v[56:59]
	v_mfma_f32_16x16x32_bf16 v[56:59], v[158:161], v[182:185], v[56:59]
	v_mfma_f32_16x16x32_bf16 v[40:43], v[158:161], v[190:193], v[40:43]
	v_mfma_f32_16x16x32_bf16 v[40:43], v[162:165], v[194:197], v[40:43]
	v_mfma_f32_16x16x32_bf16 v[44:47], v[154:157], v[194:197], v[44:47]
	v_mfma_f32_16x16x32_bf16 v[44:47], v[144:147], v[190:193], v[44:47]
	v_mfma_f32_16x16x32_bf16 v[28:31], v[144:147], v[198:201], v[28:31]
	v_mfma_f32_16x16x32_bf16 v[28:31], v[154:157], v[202:205], v[28:31]
	v_mfma_f32_16x16x32_bf16 v[24:27], v[162:165], v[202:205], v[24:27]
	v_mfma_f32_16x16x32_bf16 v[24:27], v[158:161], v[198:201], v[24:27]
	v_mfma_f32_16x16x32_bf16 v[8:11], v[158:161], v[206:209], v[8:11]
	v_mfma_f32_16x16x32_bf16 v[8:11], v[162:165], v[210:213], v[8:11]
	v_mfma_f32_16x16x32_bf16 v[12:15], v[154:157], v[210:213], v[12:15]
	v_mfma_f32_16x16x32_bf16 v[12:15], v[144:147], v[206:209], v[12:15]
	s_setprio 0
	s_setprio 1
	v_mfma_f32_16x16x32_bf16 v[52:55], v[166:169], v[182:185], v[52:55]
	v_mfma_f32_16x16x32_bf16 v[52:55], v[170:173], v[186:189], v[52:55]
	v_mfma_f32_16x16x32_bf16 v[48:51], v[178:181], v[186:189], v[48:51]
	v_mfma_f32_16x16x32_bf16 v[48:51], v[174:177], v[182:185], v[48:51]
	v_mfma_f32_16x16x32_bf16 v[32:35], v[174:177], v[190:193], v[32:35]
	v_mfma_f32_16x16x32_bf16 v[32:35], v[178:181], v[194:197], v[32:35]
	v_mfma_f32_16x16x32_bf16 v[36:39], v[170:173], v[194:197], v[36:39]
	v_mfma_f32_16x16x32_bf16 v[36:39], v[166:169], v[190:193], v[36:39]
	v_mfma_f32_16x16x32_bf16 v[20:23], v[166:169], v[198:201], v[20:23]
	v_mfma_f32_16x16x32_bf16 v[20:23], v[170:173], v[202:205], v[20:23]
	v_mfma_f32_16x16x32_bf16 v[16:19], v[178:181], v[202:205], v[16:19]
	v_mfma_f32_16x16x32_bf16 v[16:19], v[174:177], v[198:201], v[16:19]
	v_mfma_f32_16x16x32_bf16 v[0:3], v[174:177], v[206:209], v[0:3]
	v_mfma_f32_16x16x32_bf16 v[0:3], v[178:181], v[210:213], v[0:3]
	s_setprio 2
	s_barrier
; #define PG8_STAGE(bufoff, gbase, voff) do { _Pragma("unroll") for (int _i = 0; _i < 2; ++_i) \
;         __builtin_amdgcn_global_load_lds((const unsigned*)((const char*)(gbase) + (voff)[_i]), (PG8_LAS unsigned*)(lds + (bufoff) + ldsw + _i * 8192), 16, 0, 0); } while (0)
; #define PG8_LDA(dst, b, h) do { _Pragma("unroll") for (int m = 0; m < 4; ++m) _Pragma("unroll") for (int k = 0; k < 2; ++k) dst[m][k] = *(const PG8_LAS bf16x8*)(lds + PG8_SA(b, h) + aoff + m * 2048 + k * 1024); } while (0)
; #define PG8_LDB(dst, b, h) do { _Pragma("unroll") for (int n = 0; n < 2; ++n) _Pragma("unroll") for (int k = 0; k < 2; ++k) dst[n][k] = *(const PG8_LAS bf16x8*)(lds + PG8_SB(b, h) + boff + n * 2048 + k * 1024); } while (0)
; #define PG8_WAIT_V(n) asm volatile("s_waitcnt vmcnt(" #n ")" ::: "memory")
; #define PG8_WAIT_L(n) asm volatile("s_waitcnt lgkmcnt(" #n ")" ::: "memory")
; #define PG8_BAR __builtin_amdgcn_s_barrier()
; #define PG8_SCHED __builtin_amdgcn_sched_barrier(0)
; template <class Epi, class Sched, bool ALIGN_EPI = false, bool SP2 = false>
; __device__ __forceinline__ void gemm_phase(PG8_LAS unsigned char* lds, const Gemm g, const Sched& S, const Epi& E, int tid_in) {
;     ...
;             PG8_WAIT_V(8); PG8_WAIT_L(0); PG8_BAR; PG8_MMA(1, 0, At, B0); PG8_MMA(1, 1, At, B1); PG8_BAR; PG8_SCHED;
;             PG8_LDB(B0, 1, 0); PG8_LDB(B1, 1, 1); PG8_SCHED; PG8_LDA(At, 1, 0); PG8_STAGE(PG8_SA(0, 1), a2 + hstepA, voffA);
;             PG8_WAIT_V(8); PG8_WAIT_L(0); PG8_BAR; PG8_MMA(0, 0, At, B0); PG8_MMA(0, 1, At, B1); PG8_BAR; PG8_SCHED;
;             PG8_LDA(At, 1, 1); PG8_STAGE(PG8_SB(1, 0), b3, voffB); PG8_STAGE(PG8_SB(1, 1), b3 + hstep, voffB); PG8_STAGE(PG8_SA(1, 0), a3, voffA);
;             PG8_WAIT_V(8); PG8_WAIT_L(0); PG8_BAR; PG8_MMA(1, 0, At, B0); PG8_MMA(1, 1, At, B1); PG8_BAR; PG8_SCHED;
	v_mfma_f32_16x16x32_bf16 v[4:7], v[170:173], v[210:213], v[4:7]
	v_mfma_f32_16x16x32_bf16 v[4:7], v[166:169], v[206:209], v[4:7]
	s_setprio 0
	s_add_i32 s51, 0, 0x18000
	s_add_i32 s52, 0, 0x1c000
	v_add_u32_e32 v162, s51, v149
	v_add_u32_e32 v178, s52, v149
	ds_read_b128 v[144:147], v162
	ds_read_b128 v[154:157], v162 offset:1024
	ds_read_b128 v[158:161], v162 offset:2048
	ds_read_b128 v[162:165], v162 offset:3072
	ds_read_b128 v[166:169], v178
	ds_read_b128 v[170:173], v178 offset:1024
	ds_read_b128 v[174:177], v178 offset:2048
	ds_read_b128 v[178:181], v178 offset:3072
	s_add_u32 s26, s26, 0x200000
	s_addc_u32 s27, s27, 0
	s_mov_b32 m0, s36
	ds_read_b128 v[182:185], v153 offset:32768
	ds_read_b128 v[186:189], v153 offset:33792
	ds_read_b128 v[190:193], v153 offset:34816
	ds_read_b128 v[194:197], v153 offset:35840
	ds_read_b128 v[198:201], v153 offset:36864
	ds_read_b128 v[202:205], v153 offset:37888
	ds_read_b128 v[206:209], v153 offset:38912
	ds_read_b128 v[210:213], v153 offset:39936
	global_load_lds_dwordx4 v128, s[26:27]
	s_mov_b32 m0, s37
	s_nop 0
	global_load_lds_dwordx4 v132, s[26:27]
	s_waitcnt vmcnt(8)
	s_waitcnt lgkmcnt(0)
	s_barrier
	s_setprio 1
	s_waitcnt lgkmcnt(0)
	v_mfma_f32_16x16x32_bf16 v[124:127], v[144:147], v[182:185], v[124:127]
	v_mfma_f32_16x16x32_bf16 v[124:127], v[154:157], v[186:189], v[124:127]
	v_mfma_f32_16x16x32_bf16 v[120:123], v[162:165], v[186:189], v[120:123]
	v_mfma_f32_16x16x32_bf16 v[120:123], v[158:161], v[182:185], v[120:123]
	v_mfma_f32_16x16x32_bf16 v[104:107], v[158:161], v[190:193], v[104:107]
	v_mfma_f32_16x16x32_bf16 v[104:107], v[162:165], v[194:197], v[104:107]
	v_mfma_f32_16x16x32_bf16 v[108:111], v[154:157], v[194:197], v[108:111]
	v_mfma_f32_16x16x32_bf16 v[108:111], v[144:147], v[190:193], v[108:111]
	v_mfma_f32_16x16x32_bf16 v[92:95], v[144:147], v[198:201], v[92:95]
	v_mfma_f32_16x16x32_bf16 v[92:95], v[154:157], v[202:205], v[92:95]
	v_mfma_f32_16x16x32_bf16 v[88:91], v[162:165], v[202:205], v[88:91]
	v_mfma_f32_16x16x32_bf16 v[88:91], v[158:161], v[198:201], v[88:91]
	v_mfma_f32_16x16x32_bf16 v[72:75], v[158:161], v[206:209], v[72:75]
	v_mfma_f32_16x16x32_bf16 v[72:75], v[162:165], v[210:213], v[72:75]
	v_mfma_f32_16x16x32_bf16 v[76:79], v[154:157], v[210:213], v[76:79]
	v_mfma_f32_16x16x32_bf16 v[76:79], v[144:147], v[206:209], v[76:79]
	s_setprio 0
	s_setprio 1
	v_mfma_f32_16x16x32_bf16 v[116:119], v[166:169], v[182:185], v[116:119]
	v_mfma_f32_16x16x32_bf16 v[116:119], v[170:173], v[186:189], v[116:119]
	v_mfma_f32_16x16x32_bf16 v[112:115], v[178:181], v[186:189], v[112:115]
	v_mfma_f32_16x16x32_bf16 v[112:115], v[174:177], v[182:185], v[112:115]
	v_mfma_f32_16x16x32_bf16 v[96:99], v[174:177], v[190:193], v[96:99]
	v_mfma_f32_16x16x32_bf16 v[96:99], v[178:181], v[194:197], v[96:99]
	v_mfma_f32_16x16x32_bf16 v[100:103], v[170:173], v[194:197], v[100:103]
	v_mfma_f32_16x16x32_bf16 v[100:103], v[166:169], v[190:193], v[100:103]
	v_mfma_f32_16x16x32_bf16 v[84:87], v[166:169], v[198:201], v[84:87]
	v_mfma_f32_16x16x32_bf16 v[84:87], v[170:173], v[202:205], v[84:87]
	v_mfma_f32_16x16x32_bf16 v[80:83], v[178:181], v[202:205], v[80:83]
	v_mfma_f32_16x16x32_bf16 v[80:83], v[174:177], v[198:201], v[80:83]
	v_mfma_f32_16x16x32_bf16 v[64:67], v[174:177], v[206:209], v[64:67]
	v_mfma_f32_16x16x32_bf16 v[64:67], v[178:181], v[210:213], v[64:67]
	s_setprio 2
	s_barrier
	v_mfma_f32_16x16x32_bf16 v[68:71], v[170:173], v[210:213], v[68:71]
	v_mfma_f32_16x16x32_bf16 v[68:71], v[166:169], v[206:209], v[68:71]
	s_setprio 0
	s_add_i32 s26, s51, s34
	s_mov_b32 m0, s26
	ds_read_b128 v[182:185], v153 offset:49152
	ds_read_b128 v[186:189], v153 offset:50176
	ds_read_b128 v[190:193], v153 offset:51200
	ds_read_b128 v[194:197], v153 offset:52224
	ds_read_b128 v[198:201], v153 offset:53248
	ds_read_b128 v[202:205], v153 offset:54272
	ds_read_b128 v[206:209], v153 offset:55296
	ds_read_b128 v[210:213], v153 offset:56320
	global_load_lds_dwordx4 v130, s[98:99]
	s_add_i32 m0, s26, 0x2000
	s_add_u32 s24, s24, 0x200080
	s_addc_u32 s25, s25, 0
	s_add_i32 s26, s52, s34
	global_load_lds_dwordx4 v134, s[98:99]
	s_mov_b32 m0, s26
	s_nop 0
	global_load_lds_dwordx4 v130, s[24:25]
	s_add_i32 m0, s26, 0x2000
	s_nop 0
	global_load_lds_dwordx4 v134, s[24:25]
	s_mov_b32 m0, s40
	s_nop 0
	global_load_lds_dwordx4 v128, s[100:101]
	s_mov_b32 m0, s41
	s_nop 0
	global_load_lds_dwordx4 v132, s[100:101]
	s_waitcnt vmcnt(8)
	s_waitcnt lgkmcnt(0)
	s_barrier
	s_setprio 1
	s_waitcnt lgkmcnt(0)
	v_mfma_f32_16x16x32_bf16 v[60:63], v[144:147], v[182:185], v[60:63]
	v_mfma_f32_16x16x32_bf16 v[60:63], v[154:157], v[186:189], v[60:63]
	v_mfma_f32_16x16x32_bf16 v[56:59], v[162:165], v[186:189], v[56:59]
	v_mfma_f32_16x16x32_bf16 v[56:59], v[158:161], v[182:185], v[56:59]
	v_mfma_f32_16x16x32_bf16 v[40:43], v[158:161], v[190:193], v[40:43]
	v_mfma_f32_16x16x32_bf16 v[40:43], v[162:165], v[194:197], v[40:43]
	v_mfma_f32_16x16x32_bf16 v[44:47], v[154:157], v[194:197], v[44:47]
	v_mfma_f32_16x16x32_bf16 v[44:47], v[144:147], v[190:193], v[44:47]
	v_mfma_f32_16x16x32_bf16 v[28:31], v[144:147], v[198:201], v[28:31]
	v_mfma_f32_16x16x32_bf16 v[28:31], v[154:157], v[202:205], v[28:31]
	v_mfma_f32_16x16x32_bf16 v[24:27], v[162:165], v[202:205], v[24:27]
	v_mfma_f32_16x16x32_bf16 v[24:27], v[158:161], v[198:201], v[24:27]
	v_mfma_f32_16x16x32_bf16 v[8:11], v[158:161], v[206:209], v[8:11]
	v_mfma_f32_16x16x32_bf16 v[8:11], v[162:165], v[210:213], v[8:11]
	v_mfma_f32_16x16x32_bf16 v[12:15], v[154:157], v[210:213], v[12:15]
	v_mfma_f32_16x16x32_bf16 v[12:15], v[144:147], v[206:209], v[12:15]
	s_setprio 0
	s_setprio 1
	v_mfma_f32_16x16x32_bf16 v[52:55], v[166:169], v[182:185], v[52:55]
	v_mfma_f32_16x16x32_bf16 v[52:55], v[170:173], v[186:189], v[52:55]
	v_mfma_f32_16x16x32_bf16 v[48:51], v[178:181], v[186:189], v[48:51]
	v_mfma_f32_16x16x32_bf16 v[48:51], v[174:177], v[182:185], v[48:51]
	v_mfma_f32_16x16x32_bf16 v[32:35], v[174:177], v[190:193], v[32:35]
	v_mfma_f32_16x16x32_bf16 v[32:35], v[178:181], v[194:197], v[32:35]
	v_mfma_f32_16x16x32_bf16 v[36:39], v[170:173], v[194:197], v[36:39]
	v_mfma_f32_16x16x32_bf16 v[36:39], v[166:169], v[190:193], v[36:39]
	v_mfma_f32_16x16x32_bf16 v[20:23], v[166:169], v[198:201], v[20:23]
	v_mfma_f32_16x16x32_bf16 v[20:23], v[170:173], v[202:205], v[20:23]
	v_mfma_f32_16x16x32_bf16 v[16:19], v[178:181], v[202:205], v[16:19]
	v_mfma_f32_16x16x32_bf16 v[16:19], v[174:177], v[198:201], v[16:19]
	v_mfma_f32_16x16x32_bf16 v[0:3], v[174:177], v[206:209], v[0:3]
	v_mfma_f32_16x16x32_bf16 v[0:3], v[178:181], v[210:213], v[0:3]
	s_setprio 2
	s_barrier
	v_mfma_f32_16x16x32_bf16 v[4:7], v[170:173], v[210:213], v[4:7]
	v_mfma_f32_16x16x32_bf16 v[4:7], v[166:169], v[206:209], v[4:7]
	s_setprio 0
	s_add_i32 s50, s50, 2
	s_add_u32 s22, s22, 0x100
	s_addc_u32 s23, s23, 0
	s_add_u32 s48, s48, 0x100
	s_addc_u32 s49, s49, 0
	s_cmpk_gt_u32 s50, 0x7d
	s_cbranch_scc0 .LBB0_927
	s_and_b64 vcc, exec, s[10:11]
	s_cbranch_vccz .LBB0_930
	s_barrier

; #define PG8_STAGE(bufoff, gbase, voff) do { _Pragma("unroll") for (int _i = 0; _i < 2; ++_i) \
;         __builtin_amdgcn_global_load_lds((const unsigned*)((const char*)(gbase) + (voff)[_i]), (PG8_LAS unsigned*)(lds + (bufoff) + ldsw + _i * 8192), 16, 0, 0); } while (0)
; #define PG8_LDA(dst, b, h) do { _Pragma("unroll") for (int m = 0; m < 4; ++m) _Pragma("unroll") for (int k = 0; k < 2; ++k) dst[m][k] = *(const PG8_LAS bf16x8*)(lds + PG8_SA(b, h) + aoff + m * 2048 + k * 1024); } while (0)
; #define PG8_LDB(dst, b, h) do { _Pragma("unroll") for (int n = 0; n < 2; ++n) _Pragma("unroll") for (int k = 0; k < 2; ++k) dst[n][k] = *(const PG8_LAS bf16x8*)(lds + PG8_SB(b, h) + boff + n * 2048 + k * 1024); } while (0)
; #define PG8_WAIT_V(n) asm volatile("s_waitcnt vmcnt(" #n ")" ::: "memory")
; #define PG8_WAIT_L(n) asm volatile("s_waitcnt lgkmcnt(" #n ")" ::: "memory")
; #define PG8_BAR __builtin_amdgcn_s_barrier()
; #define PG8_SCHED __builtin_amdgcn_sched_barrier(0)
; template <class Epi, class Sched, bool ALIGN_EPI = false, bool SP2 = false>
; __device__ __forceinline__ void gemm_phase(PG8_LAS unsigned char* lds, const Gemm g, const Sched& S, const Epi& E, int tid_in) {
;     ...
;         for (int t = 0; t < nt; t += 2) {
;             const bool last = (t == nt - 2);
;             const char* a1 = cA + (size_t)(t + 1) * kstep;
;             const char* a2 = last ? nA : cA + (size_t)(t + 2) * kstep; const char* b2 = last ? nB : cB + (size_t)(t + 2) * kstep;
;             const char* a3 = a2 + kstep; const char* b3 = b2 + kstep;
;             if (last && has_next) S.a_ready(nxt);
;             if constexpr (SP2) {
;             PG8_LDB(B0, 0, 0); PG8_LDB(B1, 0, 1); PG8_SCHED; PG8_LDA(At, 0, 0); PG8_STAGE(PG8_SA(1, 1), a1 + hstepA, voffA);
;             PG8_WAIT_V(8); PG8_WAIT_L(0); PG8_BAR; PG8_MMA(0, 0, At, B0); PG8_MMA(0, 1, At, B1); PG8_BAR; PG8_SCHED;
;             PG8_LDA(At, 0, 1); PG8_STAGE(PG8_SB(0, 0), b2, voffB); PG8_STAGE(PG8_SB(0, 1), b2 + hstep, voffB); PG8_STAGE(PG8_SA(0, 0), a2, voffA);
;             PG8_WAIT_V(8); PG8_WAIT_L(0); PG8_BAR; PG8_MMA(1, 0, At, B0); PG8_MMA(1, 1, At, B1); PG8_BAR; PG8_SCHED;
.LBB0_952:
	ds_read_b128 v[144:147], v155
	ds_read_b128 v[148:151], v155 offset:1024
	ds_read_b128 v[158:161], v155 offset:2048
	ds_read_b128 v[162:165], v155 offset:3072
	ds_read_b128 v[166:169], v156
	ds_read_b128 v[170:173], v156 offset:1024
	ds_read_b128 v[174:177], v156 offset:2048
	ds_read_b128 v[178:181], v156 offset:3072
	s_add_u32 s28, s26, 0xfff00080
	s_addc_u32 s29, s27, -1
	s_cmp_eq_u32 s54, 60
	s_cselect_b32 s31, s19, s29
	s_cselect_b32 s30, s50, s28
	s_cselect_b32 s29, s17, s53
	s_cselect_b32 s28, s51, s52
	s_add_i32 m0, s25, 0xc000
	ds_read_b128 v[182:185], v157
	ds_read_b128 v[186:189], v157 offset:1024
	ds_read_b128 v[190:193], v157 offset:2048
	ds_read_b128 v[194:197], v157 offset:3072
	ds_read_b128 v[198:201], v157 offset:4096
	ds_read_b128 v[202:205], v157 offset:5120
	ds_read_b128 v[206:209], v157 offset:6144
	ds_read_b128 v[210:213], v157 offset:7168
	global_load_lds_dwordx4 v136, s[26:27]
	s_add_i32 m0, s25, 0xe000
	s_nop 0
	global_load_lds_dwordx4 v138, s[26:27]
	s_waitcnt vmcnt(8)
	s_waitcnt lgkmcnt(0)
	s_barrier
	s_setprio 1
	s_waitcnt lgkmcnt(0)
	v_mfma_f32_16x16x32_bf16 v[124:127], v[144:147], v[182:185], v[124:127]
	v_mfma_f32_16x16x32_bf16 v[124:127], v[148:151], v[186:189], v[124:127]
	v_mfma_f32_16x16x32_bf16 v[120:123], v[162:165], v[186:189], v[120:123]
	v_mfma_f32_16x16x32_bf16 v[120:123], v[158:161], v[182:185], v[120:123]
	v_mfma_f32_16x16x32_bf16 v[104:107], v[158:161], v[190:193], v[104:107]
	v_mfma_f32_16x16x32_bf16 v[104:107], v[162:165], v[194:197], v[104:107]
	v_mfma_f32_16x16x32_bf16 v[108:111], v[148:151], v[194:197], v[108:111]
	v_mfma_f32_16x16x32_bf16 v[108:111], v[144:147], v[190:193], v[108:111]
	v_mfma_f32_16x16x32_bf16 v[92:95], v[144:147], v[198:201], v[92:95]
	v_mfma_f32_16x16x32_bf16 v[92:95], v[148:151], v[202:205], v[92:95]
	v_mfma_f32_16x16x32_bf16 v[88:91], v[162:165], v[202:205], v[88:91]
	v_mfma_f32_16x16x32_bf16 v[88:91], v[158:161], v[198:201], v[88:91]
	v_mfma_f32_16x16x32_bf16 v[72:75], v[158:161], v[206:209], v[72:75]
	v_mfma_f32_16x16x32_bf16 v[72:75], v[162:165], v[210:213], v[72:75]
	v_mfma_f32_16x16x32_bf16 v[76:79], v[148:151], v[210:213], v[76:79]
	v_mfma_f32_16x16x32_bf16 v[76:79], v[144:147], v[206:209], v[76:79]
	s_setprio 0
	s_setprio 1
	v_mfma_f32_16x16x32_bf16 v[116:119], v[166:169], v[182:185], v[116:119]
	v_mfma_f32_16x16x32_bf16 v[116:119], v[170:173], v[186:189], v[116:119]
	v_mfma_f32_16x16x32_bf16 v[112:115], v[178:181], v[186:189], v[112:115]
	v_mfma_f32_16x16x32_bf16 v[112:115], v[174:177], v[182:185], v[112:115]
	v_mfma_f32_16x16x32_bf16 v[96:99], v[174:177], v[190:193], v[96:99]
	v_mfma_f32_16x16x32_bf16 v[96:99], v[178:181], v[194:197], v[96:99]
	v_mfma_f32_16x16x32_bf16 v[100:103], v[170:173], v[194:197], v[100:103]
	v_mfma_f32_16x16x32_bf16 v[100:103], v[166:169], v[190:193], v[100:103]
	v_mfma_f32_16x16x32_bf16 v[84:87], v[166:169], v[198:201], v[84:87]
	v_mfma_f32_16x16x32_bf16 v[84:87], v[170:173], v[202:205], v[84:87]
	v_mfma_f32_16x16x32_bf16 v[80:83], v[178:181], v[202:205], v[80:83]
	v_mfma_f32_16x16x32_bf16 v[80:83], v[174:177], v[198:201], v[80:83]
	v_mfma_f32_16x16x32_bf16 v[64:67], v[174:177], v[206:209], v[64:67]
	v_mfma_f32_16x16x32_bf16 v[64:67], v[178:181], v[210:213], v[64:67]
	s_setprio 2
	s_barrier
	v_mfma_f32_16x16x32_bf16 v[68:71], v[170:173], v[210:213], v[68:71]
	v_mfma_f32_16x16x32_bf16 v[68:71], v[166:169], v[206:209], v[68:71]
	s_setprio 0
	s_add_u32 s98, s28, 0x80
	s_addc_u32 s99, s29, 0
	s_add_u32 s100, s30, 0x80
	s_addc_u32 s101, s31, 0
	s_add_i32 s55, s47, s38
	s_mov_b32 m0, s55
	ds_read_b128 v[182:185], v157 offset:16384
	ds_read_b128 v[186:189], v157 offset:17408
	ds_read_b128 v[190:193], v157 offset:18432
	ds_read_b128 v[194:197], v157 offset:19456
	ds_read_b128 v[198:201], v157 offset:20480
	ds_read_b128 v[202:205], v157 offset:21504
	ds_read_b128 v[206:209], v157 offset:22528
	ds_read_b128 v[210:213], v157 offset:23552
	global_load_lds_dwordx4 v130, s[28:29]
	s_add_i32 m0, s55, 0x2000
	s_add_u32 s56, s28, 0x100000
	s_addc_u32 s57, s29, 0
	s_add_i32 s55, s48, s38
	global_load_lds_dwordx4 v134, s[28:29]
	s_mov_b32 m0, s55
	s_nop 0
	global_load_lds_dwordx4 v130, s[56:57]
	s_add_i32 m0, s55, 0x2000
	s_nop 0
	global_load_lds_dwordx4 v134, s[56:57]
	s_mov_b32 m0, s25
	s_nop 0
	global_load_lds_dwordx4 v128, s[30:31]
	s_mov_b32 m0, s39
	s_nop 0
	global_load_lds_dwordx4 v132, s[30:31]
	s_waitcnt vmcnt(8)
	s_waitcnt lgkmcnt(0)
	s_barrier
	s_setprio 1
	s_waitcnt lgkmcnt(0)
	v_mfma_f32_16x16x32_bf16 v[60:63], v[144:147], v[182:185], v[60:63]
	v_mfma_f32_16x16x32_bf16 v[60:63], v[148:151], v[186:189], v[60:63]
	v_mfma_f32_16x16x32_bf16 v[56:59], v[162:165], v[186:189], v[56:59]
	v_mfma_f32_16x16x32_bf16 v[56:59], v[158:161], v[182:185], v[56:59]
	v_mfma_f32_16x16x32_bf16 v[40:43], v[158:161], v[190:193], v[40:43]
	v_mfma_f32_16x16x32_bf16 v[40:43], v[162:165], v[194:197], v[40:43]
	v_mfma_f32_16x16x32_bf16 v[44:47], v[148:151], v[194:197], v[44:47]
	v_mfma_f32_16x16x32_bf16 v[44:47], v[144:147], v[190:193], v[44:47]
	v_mfma_f32_16x16x32_bf16 v[28:31], v[144:147], v[198:201], v[28:31]
	v_mfma_f32_16x16x32_bf16 v[28:31], v[148:151], v[202:205], v[28:31]
	v_mfma_f32_16x16x32_bf16 v[24:27], v[162:165], v[202:205], v[24:27]
	v_mfma_f32_16x16x32_bf16 v[24:27], v[158:161], v[198:201], v[24:27]
	v_mfma_f32_16x16x32_bf16 v[8:11], v[158:161], v[206:209], v[8:11]
	v_mfma_f32_16x16x32_bf16 v[8:11], v[162:165], v[210:213], v[8:11]
	v_mfma_f32_16x16x32_bf16 v[12:15], v[148:151], v[210:213], v[12:15]
	v_mfma_f32_16x16x32_bf16 v[12:15], v[144:147], v[206:209], v[12:15]
	s_setprio 0
	s_setprio 1
	v_mfma_f32_16x16x32_bf16 v[52:55], v[166:169], v[182:185], v[52:55]
	v_mfma_f32_16x16x32_bf16 v[52:55], v[170:173], v[186:189], v[52:55]
	v_mfma_f32_16x16x32_bf16 v[48:51], v[178:181], v[186:189], v[48:51]
	v_mfma_f32_16x16x32_bf16 v[48:51], v[174:177], v[182:185], v[48:51]
	v_mfma_f32_16x16x32_bf16 v[32:35], v[174:177], v[190:193], v[32:35]
	v_mfma_f32_16x16x32_bf16 v[32:35], v[178:181], v[194:197], v[32:35]
	v_mfma_f32_16x16x32_bf16 v[36:39], v[170:173], v[194:197], v[36:39]
	v_mfma_f32_16x16x32_bf16 v[36:39], v[166:169], v[190:193], v[36:39]
	v_mfma_f32_16x16x32_bf16 v[20:23], v[166:169], v[198:201], v[20:23]
	v_mfma_f32_16x16x32_bf16 v[20:23], v[170:173], v[202:205], v[20:23]
	v_mfma_f32_16x16x32_bf16 v[16:19], v[178:181], v[202:205], v[16:19]
	v_mfma_f32_16x16x32_bf16 v[16:19], v[174:177], v[198:201], v[16:19]
	v_mfma_f32_16x16x32_bf16 v[0:3], v[174:177], v[206:209], v[0:3]
	v_mfma_f32_16x16x32_bf16 v[0:3], v[178:181], v[210:213], v[0:3]
	s_setprio 2
	s_barrier
; #define PG8_STAGE(bufoff, gbase, voff) do { _Pragma("unroll") for (int _i = 0; _i < 2; ++_i) \
;         __builtin_amdgcn_global_load_lds((const unsigned*)((const char*)(gbase) + (voff)[_i]), (PG8_LAS unsigned*)(lds + (bufoff) + ldsw + _i * 8192), 16, 0, 0); } while (0)
; #define PG8_LDA(dst, b, h) do { _Pragma("unroll") for (int m = 0; m < 4; ++m) _Pragma("unroll") for (int k = 0; k < 2; ++k) dst[m][k] = *(const PG8_LAS bf16x8*)(lds + PG8_SA(b, h) + aoff + m * 2048 + k * 1024); } while (0)
; #define PG8_LDB(dst, b, h) do { _Pragma("unroll") for (int n = 0; n < 2; ++n) _Pragma("unroll") for (int k = 0; k < 2; ++k) dst[n][k] = *(const PG8_LAS bf16x8*)(lds + PG8_SB(b, h) + boff + n * 2048 + k * 1024); } while (0)
; #define PG8_WAIT_V(n) asm volatile("s_waitcnt vmcnt(" #n ")" ::: "memory")
; #define PG8_WAIT_L(n) asm volatile("s_waitcnt lgkmcnt(" #n ")" ::: "memory")
; #define PG8_BAR __builtin_amdgcn_s_barrier()
; #define PG8_SCHED __builtin_amdgcn_sched_barrier(0)
; template <class Epi, class Sched, bool ALIGN_EPI = false, bool SP2 = false>
; __device__ __forceinline__ void gemm_phase(PG8_LAS unsigned char* lds, const Gemm g, const Sched& S, const Epi& E, int tid_in) {
;     ...
;             PG8_WAIT_V(8); PG8_WAIT_L(0); PG8_BAR; PG8_MMA(1, 0, At, B0); PG8_MMA(1, 1, At, B1); PG8_BAR; PG8_SCHED;
;             PG8_LDB(B0, 1, 0); PG8_LDB(B1, 1, 1); PG8_SCHED; PG8_LDA(At, 1, 0); PG8_STAGE(PG8_SA(0, 1), a2 + hstepA, voffA);
;             PG8_WAIT_V(8); PG8_WAIT_L(0); PG8_BAR; PG8_MMA(0, 0, At, B0); PG8_MMA(0, 1, At, B1); PG8_BAR; PG8_SCHED;
;             PG8_LDA(At, 1, 1); PG8_STAGE(PG8_SB(1, 0), b3, voffB); PG8_STAGE(PG8_SB(1, 1), b3 + hstep, voffB); PG8_STAGE(PG8_SA(1, 0), a3, voffA);
;             PG8_WAIT_V(8); PG8_WAIT_L(0); PG8_BAR; PG8_MMA(1, 0, At, B0); PG8_MMA(1, 1, At, B1); PG8_BAR; PG8_SCHED;
	v_mfma_f32_16x16x32_bf16 v[4:7], v[170:173], v[210:213], v[4:7]
	v_mfma_f32_16x16x32_bf16 v[4:7], v[166:169], v[206:209], v[4:7]
	s_setprio 0
	s_add_i32 s55, 0, 0x18000
	s_add_i32 s56, 0, 0x1c000
	v_add_u32_e32 v162, s55, v153
	v_add_u32_e32 v178, s56, v153
	ds_read_b128 v[144:147], v162
	ds_read_b128 v[148:151], v162 offset:1024
	ds_read_b128 v[158:161], v162 offset:2048
	ds_read_b128 v[162:165], v162 offset:3072
	ds_read_b128 v[166:169], v178
	ds_read_b128 v[170:173], v178 offset:1024
	ds_read_b128 v[174:177], v178 offset:2048
	ds_read_b128 v[178:181], v178 offset:3072
	s_add_u32 s30, s30, 0x100000
	s_addc_u32 s31, s31, 0
	s_mov_b32 m0, s40
	ds_read_b128 v[182:185], v157 offset:32768
	ds_read_b128 v[186:189], v157 offset:33792
	ds_read_b128 v[190:193], v157 offset:34816
	ds_read_b128 v[194:197], v157 offset:35840
	ds_read_b128 v[198:201], v157 offset:36864
	ds_read_b128 v[202:205], v157 offset:37888
	ds_read_b128 v[206:209], v157 offset:38912
	ds_read_b128 v[210:213], v157 offset:39936
	global_load_lds_dwordx4 v128, s[30:31]
	s_mov_b32 m0, s41
	s_nop 0
	global_load_lds_dwordx4 v132, s[30:31]
	s_waitcnt vmcnt(8)
	s_waitcnt lgkmcnt(0)
	s_barrier
	s_setprio 1
	s_waitcnt lgkmcnt(0)
	v_mfma_f32_16x16x32_bf16 v[124:127], v[144:147], v[182:185], v[124:127]
	v_mfma_f32_16x16x32_bf16 v[124:127], v[148:151], v[186:189], v[124:127]
	v_mfma_f32_16x16x32_bf16 v[120:123], v[162:165], v[186:189], v[120:123]
	v_mfma_f32_16x16x32_bf16 v[120:123], v[158:161], v[182:185], v[120:123]
	v_mfma_f32_16x16x32_bf16 v[104:107], v[158:161], v[190:193], v[104:107]
	v_mfma_f32_16x16x32_bf16 v[104:107], v[162:165], v[194:197], v[104:107]
	v_mfma_f32_16x16x32_bf16 v[108:111], v[148:151], v[194:197], v[108:111]
	v_mfma_f32_16x16x32_bf16 v[108:111], v[144:147], v[190:193], v[108:111]
	v_mfma_f32_16x16x32_bf16 v[92:95], v[144:147], v[198:201], v[92:95]
	v_mfma_f32_16x16x32_bf16 v[92:95], v[148:151], v[202:205], v[92:95]
	v_mfma_f32_16x16x32_bf16 v[88:91], v[162:165], v[202:205], v[88:91]
	v_mfma_f32_16x16x32_bf16 v[88:91], v[158:161], v[198:201], v[88:91]
	v_mfma_f32_16x16x32_bf16 v[72:75], v[158:161], v[206:209], v[72:75]
	v_mfma_f32_16x16x32_bf16 v[72:75], v[162:165], v[210:213], v[72:75]
	v_mfma_f32_16x16x32_bf16 v[76:79], v[148:151], v[210:213], v[76:79]
	v_mfma_f32_16x16x32_bf16 v[76:79], v[144:147], v[206:209], v[76:79]
	s_setprio 0
	s_setprio 1
	v_mfma_f32_16x16x32_bf16 v[116:119], v[166:169], v[182:185], v[116:119]
	v_mfma_f32_16x16x32_bf16 v[116:119], v[170:173], v[186:189], v[116:119]
	v_mfma_f32_16x16x32_bf16 v[112:115], v[178:181], v[186:189], v[112:115]
	v_mfma_f32_16x16x32_bf16 v[112:115], v[174:177], v[182:185], v[112:115]
	v_mfma_f32_16x16x32_bf16 v[96:99], v[174:177], v[190:193], v[96:99]
	v_mfma_f32_16x16x32_bf16 v[96:99], v[178:181], v[194:197], v[96:99]
	v_mfma_f32_16x16x32_bf16 v[100:103], v[170:173], v[194:197], v[100:103]
	v_mfma_f32_16x16x32_bf16 v[100:103], v[166:169], v[190:193], v[100:103]
	v_mfma_f32_16x16x32_bf16 v[84:87], v[166:169], v[198:201], v[84:87]
	v_mfma_f32_16x16x32_bf16 v[84:87], v[170:173], v[202:205], v[84:87]
	v_mfma_f32_16x16x32_bf16 v[80:83], v[178:181], v[202:205], v[80:83]
	v_mfma_f32_16x16x32_bf16 v[80:83], v[174:177], v[198:201], v[80:83]
	v_mfma_f32_16x16x32_bf16 v[64:67], v[174:177], v[206:209], v[64:67]
	v_mfma_f32_16x16x32_bf16 v[64:67], v[178:181], v[210:213], v[64:67]
	s_setprio 2
	s_barrier
	v_mfma_f32_16x16x32_bf16 v[68:71], v[170:173], v[210:213], v[68:71]
	v_mfma_f32_16x16x32_bf16 v[68:71], v[166:169], v[206:209], v[68:71]
	s_setprio 0
	s_add_i32 s30, s55, s38
	s_mov_b32 m0, s30
	ds_read_b128 v[182:185], v157 offset:49152
	ds_read_b128 v[186:189], v157 offset:50176
	ds_read_b128 v[190:193], v157 offset:51200
	ds_read_b128 v[194:197], v157 offset:52224
	ds_read_b128 v[198:201], v157 offset:53248
	ds_read_b128 v[202:205], v157 offset:54272
	ds_read_b128 v[206:209], v157 offset:55296
	ds_read_b128 v[210:213], v157 offset:56320
	global_load_lds_dwordx4 v130, s[98:99]
	s_add_i32 m0, s30, 0x2000
	s_add_u32 s28, s28, 0x100080
	s_addc_u32 s29, s29, 0
	s_add_i32 s30, s56, s38
	global_load_lds_dwordx4 v134, s[98:99]
	s_mov_b32 m0, s30
	s_nop 0
	global_load_lds_dwordx4 v130, s[28:29]
	s_add_i32 m0, s30, 0x2000
	s_nop 0
	global_load_lds_dwordx4 v134, s[28:29]
	s_mov_b32 m0, s44
	s_nop 0
	global_load_lds_dwordx4 v128, s[100:101]
	s_mov_b32 m0, s45
	s_nop 0
	global_load_lds_dwordx4 v132, s[100:101]
	s_waitcnt vmcnt(8)
	s_waitcnt lgkmcnt(0)
	s_barrier
	s_setprio 1
	s_waitcnt lgkmcnt(0)
	v_mfma_f32_16x16x32_bf16 v[60:63], v[144:147], v[182:185], v[60:63]
	v_mfma_f32_16x16x32_bf16 v[60:63], v[148:151], v[186:189], v[60:63]
	v_mfma_f32_16x16x32_bf16 v[56:59], v[162:165], v[186:189], v[56:59]
	v_mfma_f32_16x16x32_bf16 v[56:59], v[158:161], v[182:185], v[56:59]
	v_mfma_f32_16x16x32_bf16 v[40:43], v[158:161], v[190:193], v[40:43]
	v_mfma_f32_16x16x32_bf16 v[40:43], v[162:165], v[194:197], v[40:43]
	v_mfma_f32_16x16x32_bf16 v[44:47], v[148:151], v[194:197], v[44:47]
	v_mfma_f32_16x16x32_bf16 v[44:47], v[144:147], v[190:193], v[44:47]
	v_mfma_f32_16x16x32_bf16 v[28:31], v[144:147], v[198:201], v[28:31]
	v_mfma_f32_16x16x32_bf16 v[28:31], v[148:151], v[202:205], v[28:31]
	v_mfma_f32_16x16x32_bf16 v[24:27], v[162:165], v[202:205], v[24:27]
	v_mfma_f32_16x16x32_bf16 v[24:27], v[158:161], v[198:201], v[24:27]
	v_mfma_f32_16x16x32_bf16 v[8:11], v[158:161], v[206:209], v[8:11]
	v_mfma_f32_16x16x32_bf16 v[8:11], v[162:165], v[210:213], v[8:11]
	v_mfma_f32_16x16x32_bf16 v[12:15], v[148:151], v[210:213], v[12:15]
	v_mfma_f32_16x16x32_bf16 v[12:15], v[144:147], v[206:209], v[12:15]
	s_setprio 0
	s_setprio 1
	v_mfma_f32_16x16x32_bf16 v[52:55], v[166:169], v[182:185], v[52:55]
	v_mfma_f32_16x16x32_bf16 v[52:55], v[170:173], v[186:189], v[52:55]
	v_mfma_f32_16x16x32_bf16 v[48:51], v[178:181], v[186:189], v[48:51]
	v_mfma_f32_16x16x32_bf16 v[48:51], v[174:177], v[182:185], v[48:51]
	v_mfma_f32_16x16x32_bf16 v[32:35], v[174:177], v[190:193], v[32:35]
	v_mfma_f32_16x16x32_bf16 v[32:35], v[178:181], v[194:197], v[32:35]
	v_mfma_f32_16x16x32_bf16 v[36:39], v[170:173], v[194:197], v[36:39]
	v_mfma_f32_16x16x32_bf16 v[36:39], v[166:169], v[190:193], v[36:39]
	v_mfma_f32_16x16x32_bf16 v[20:23], v[166:169], v[198:201], v[20:23]
	v_mfma_f32_16x16x32_bf16 v[20:23], v[170:173], v[202:205], v[20:23]
	v_mfma_f32_16x16x32_bf16 v[16:19], v[178:181], v[202:205], v[16:19]
	v_mfma_f32_16x16x32_bf16 v[16:19], v[174:177], v[198:201], v[16:19]
	v_mfma_f32_16x16x32_bf16 v[0:3], v[174:177], v[206:209], v[0:3]
	v_mfma_f32_16x16x32_bf16 v[0:3], v[178:181], v[210:213], v[0:3]
	s_setprio 2
	s_barrier
	v_mfma_f32_16x16x32_bf16 v[4:7], v[170:173], v[210:213], v[4:7]
	v_mfma_f32_16x16x32_bf16 v[4:7], v[166:169], v[206:209], v[4:7]
	s_setprio 0
	s_add_i32 s54, s54, 2
	s_add_u32 s26, s26, 0x100
	s_addc_u32 s27, s27, 0
	s_add_u32 s52, s52, 0x100
	s_addc_u32 s53, s53, 0
	s_cmp_gt_u32 s54, 61
	s_cbranch_scc0 .LBB0_952
	s_and_b64 vcc, exec, s[12:13]
	s_cbranch_vccz .LBB0_955
	s_barrier

; #define PG8_STAGE(bufoff, gbase, voff) do { _Pragma("unroll") for (int _i = 0; _i < 2; ++_i) \
;         __builtin_amdgcn_global_load_lds((const unsigned*)((const char*)(gbase) + (voff)[_i]), (PG8_LAS unsigned*)(lds + (bufoff) + ldsw + _i * 8192), 16, 0, 0); } while (0)
; #define PG8_LDA(dst, b, h) do { _Pragma("unroll") for (int m = 0; m < 4; ++m) _Pragma("unroll") for (int k = 0; k < 2; ++k) dst[m][k] = *(const PG8_LAS bf16x8*)(lds + PG8_SA(b, h) + aoff + m * 2048 + k * 1024); } while (0)
; #define PG8_LDB(dst, b, h) do { _Pragma("unroll") for (int n = 0; n < 2; ++n) _Pragma("unroll") for (int k = 0; k < 2; ++k) dst[n][k] = *(const PG8_LAS bf16x8*)(lds + PG8_SB(b, h) + boff + n * 2048 + k * 1024); } while (0)
; #define PG8_WAIT_V(n) asm volatile("s_waitcnt vmcnt(" #n ")" ::: "memory")
; #define PG8_WAIT_L(n) asm volatile("s_waitcnt lgkmcnt(" #n ")" ::: "memory")
; #define PG8_BAR __builtin_amdgcn_s_barrier()
; #define PG8_SCHED __builtin_amdgcn_sched_barrier(0)
; template <class Epi, class Sched, bool ALIGN_EPI = false, bool SP2 = false>
; __device__ __forceinline__ void gemm_phase(PG8_LAS unsigned char* lds, const Gemm g, const Sched& S, const Epi& E, int tid_in) {
;     ...
;         for (int t = 0; t < nt; t += 2) {
;             const bool last = (t == nt - 2);
;             const char* a1 = cA + (size_t)(t + 1) * kstep;
;             const char* a2 = last ? nA : cA + (size_t)(t + 2) * kstep; const char* b2 = last ? nB : cB + (size_t)(t + 2) * kstep;
;             const char* a3 = a2 + kstep; const char* b3 = b2 + kstep;
;             if (last && has_next) S.a_ready(nxt);
;             if constexpr (SP2) {
;             PG8_LDB(B0, 0, 0); PG8_LDB(B1, 0, 1); PG8_SCHED; PG8_LDA(At, 0, 0); PG8_STAGE(PG8_SA(1, 1), a1 + hstepA, voffA);
;             PG8_WAIT_V(8); PG8_WAIT_L(0); PG8_BAR; PG8_MMA(0, 0, At, B0); PG8_MMA(0, 1, At, B1); PG8_BAR; PG8_SCHED;
;             PG8_LDA(At, 0, 1); PG8_STAGE(PG8_SB(0, 0), b2, voffB); PG8_STAGE(PG8_SB(0, 1), b2 + hstep, voffB); PG8_STAGE(PG8_SA(0, 0), a2, voffA);
;             PG8_WAIT_V(8); PG8_WAIT_L(0); PG8_BAR; PG8_MMA(1, 0, At, B0); PG8_MMA(1, 1, At, B1); PG8_BAR; PG8_SCHED;
.LBB0_1031:
	ds_read_b128 v[128:131], v167
	ds_read_b128 v[132:135], v167 offset:1024
	ds_read_b128 v[152:155], v167 offset:2048
	ds_read_b128 v[156:159], v167 offset:3072
	ds_read_b128 v[160:163], v168
	ds_read_b128 v[170:173], v168 offset:1024
	ds_read_b128 v[174:177], v168 offset:2048
	ds_read_b128 v[178:181], v168 offset:3072
	s_add_u32 s36, s34, 0xfff00080
	s_addc_u32 s37, s35, -1
	s_cmp_eq_u32 s61, 60
	s_cselect_b32 s39, s25, s37
	s_cselect_b32 s38, s57, s36
	s_cselect_b32 s37, s23, s60
	s_cselect_b32 s36, s58, s59
	s_add_i32 m0, s31, 0xc000
	ds_read_b128 v[182:185], v169
	ds_read_b128 v[186:189], v169 offset:1024
	ds_read_b128 v[190:193], v169 offset:2048
	ds_read_b128 v[194:197], v169 offset:3072
	ds_read_b128 v[198:201], v169 offset:4096
	ds_read_b128 v[202:205], v169 offset:5120
	ds_read_b128 v[206:209], v169 offset:6144
	ds_read_b128 v[210:213], v169 offset:7168
	global_load_lds_dwordx4 v144, s[34:35]
	s_add_i32 m0, s31, 0xe000
	s_nop 0
	global_load_lds_dwordx4 v146, s[34:35]
	s_waitcnt vmcnt(8)
	s_waitcnt lgkmcnt(0)
	s_barrier
	s_setprio 1
	s_waitcnt lgkmcnt(0)
	v_mfma_f32_16x16x32_bf16 v[124:127], v[128:131], v[182:185], v[124:127]
	v_mfma_f32_16x16x32_bf16 v[124:127], v[132:135], v[186:189], v[124:127]
	v_mfma_f32_16x16x32_bf16 v[120:123], v[156:159], v[186:189], v[120:123]
	v_mfma_f32_16x16x32_bf16 v[120:123], v[152:155], v[182:185], v[120:123]
	v_mfma_f32_16x16x32_bf16 v[112:115], v[152:155], v[190:193], v[112:115]
	v_mfma_f32_16x16x32_bf16 v[112:115], v[156:159], v[194:197], v[112:115]
	v_mfma_f32_16x16x32_bf16 v[116:119], v[132:135], v[194:197], v[116:119]
	v_mfma_f32_16x16x32_bf16 v[116:119], v[128:131], v[190:193], v[116:119]
	v_mfma_f32_16x16x32_bf16 v[108:111], v[128:131], v[198:201], v[108:111]
	v_mfma_f32_16x16x32_bf16 v[108:111], v[132:135], v[202:205], v[108:111]
	v_mfma_f32_16x16x32_bf16 v[104:107], v[156:159], v[202:205], v[104:107]
	v_mfma_f32_16x16x32_bf16 v[104:107], v[152:155], v[198:201], v[104:107]
	v_mfma_f32_16x16x32_bf16 v[96:99], v[152:155], v[206:209], v[96:99]
	v_mfma_f32_16x16x32_bf16 v[96:99], v[156:159], v[210:213], v[96:99]
	v_mfma_f32_16x16x32_bf16 v[100:103], v[132:135], v[210:213], v[100:103]
	v_mfma_f32_16x16x32_bf16 v[100:103], v[128:131], v[206:209], v[100:103]
	s_setprio 0
	s_setprio 1
	v_mfma_f32_16x16x32_bf16 v[68:71], v[160:163], v[182:185], v[68:71]
	v_mfma_f32_16x16x32_bf16 v[68:71], v[170:173], v[186:189], v[68:71]
	v_mfma_f32_16x16x32_bf16 v[60:63], v[178:181], v[186:189], v[60:63]
	v_mfma_f32_16x16x32_bf16 v[60:63], v[174:177], v[182:185], v[60:63]
	v_mfma_f32_16x16x32_bf16 v[48:51], v[174:177], v[190:193], v[48:51]
	v_mfma_f32_16x16x32_bf16 v[48:51], v[178:181], v[194:197], v[48:51]
	v_mfma_f32_16x16x32_bf16 v[52:55], v[170:173], v[194:197], v[52:55]
	v_mfma_f32_16x16x32_bf16 v[52:55], v[160:163], v[190:193], v[52:55]
	v_mfma_f32_16x16x32_bf16 v[44:47], v[160:163], v[198:201], v[44:47]
	v_mfma_f32_16x16x32_bf16 v[44:47], v[170:173], v[202:205], v[44:47]
	v_mfma_f32_16x16x32_bf16 v[40:43], v[178:181], v[202:205], v[40:43]
	v_mfma_f32_16x16x32_bf16 v[40:43], v[174:177], v[198:201], v[40:43]
	v_mfma_f32_16x16x32_bf16 v[32:35], v[174:177], v[206:209], v[32:35]
	v_mfma_f32_16x16x32_bf16 v[32:35], v[178:181], v[210:213], v[32:35]
	s_setprio 2
	s_barrier
	v_mfma_f32_16x16x32_bf16 v[36:39], v[170:173], v[210:213], v[36:39]
	v_mfma_f32_16x16x32_bf16 v[36:39], v[160:163], v[206:209], v[36:39]
	s_setprio 0
	s_add_u32 s98, s36, 0x80
	s_addc_u32 s99, s37, 0
	s_add_u32 s100, s38, 0x80
	s_addc_u32 s101, s39, 0
	s_add_i32 s62, s54, s43
	s_mov_b32 m0, s62
	ds_read_b128 v[182:185], v169 offset:16384
	ds_read_b128 v[186:189], v169 offset:17408
	ds_read_b128 v[190:193], v169 offset:18432
	ds_read_b128 v[194:197], v169 offset:19456
	ds_read_b128 v[198:201], v169 offset:20480
	ds_read_b128 v[202:205], v169 offset:21504
	ds_read_b128 v[206:209], v169 offset:22528
	ds_read_b128 v[210:213], v169 offset:23552
	global_load_lds_dwordx4 v138, s[36:37]
	s_add_i32 m0, s62, 0x2000
	s_add_u32 s62, s36, 0x100000
	s_addc_u32 s63, s37, 0
	s_add_i32 s64, s55, s43
	global_load_lds_dwordx4 v142, s[36:37]
	s_mov_b32 m0, s64
	s_nop 0
	global_load_lds_dwordx4 v138, s[62:63]
	s_add_i32 m0, s64, 0x2000
	s_nop 0
	global_load_lds_dwordx4 v142, s[62:63]
	s_mov_b32 m0, s31
	s_nop 0
	global_load_lds_dwordx4 v136, s[38:39]
	s_mov_b32 m0, s44
	s_nop 0
	global_load_lds_dwordx4 v140, s[38:39]
	s_waitcnt vmcnt(8)
	s_waitcnt lgkmcnt(0)
	s_barrier
	s_setprio 1
	s_waitcnt lgkmcnt(0)
	v_mfma_f32_16x16x32_bf16 v[92:95], v[128:131], v[182:185], v[92:95]
	v_mfma_f32_16x16x32_bf16 v[92:95], v[132:135], v[186:189], v[92:95]
	v_mfma_f32_16x16x32_bf16 v[88:91], v[156:159], v[186:189], v[88:91]
	v_mfma_f32_16x16x32_bf16 v[88:91], v[152:155], v[182:185], v[88:91]
	v_mfma_f32_16x16x32_bf16 v[80:83], v[152:155], v[190:193], v[80:83]
	v_mfma_f32_16x16x32_bf16 v[80:83], v[156:159], v[194:197], v[80:83]
	v_mfma_f32_16x16x32_bf16 v[84:87], v[132:135], v[194:197], v[84:87]
	v_mfma_f32_16x16x32_bf16 v[84:87], v[128:131], v[190:193], v[84:87]
	v_mfma_f32_16x16x32_bf16 v[76:79], v[128:131], v[198:201], v[76:79]
	v_mfma_f32_16x16x32_bf16 v[76:79], v[132:135], v[202:205], v[76:79]
	v_mfma_f32_16x16x32_bf16 v[72:75], v[156:159], v[202:205], v[72:75]
	v_mfma_f32_16x16x32_bf16 v[72:75], v[152:155], v[198:201], v[72:75]
	v_mfma_f32_16x16x32_bf16 v[56:59], v[152:155], v[206:209], v[56:59]
	v_mfma_f32_16x16x32_bf16 v[56:59], v[156:159], v[210:213], v[56:59]
	v_mfma_f32_16x16x32_bf16 v[64:67], v[132:135], v[210:213], v[64:67]
	v_mfma_f32_16x16x32_bf16 v[64:67], v[128:131], v[206:209], v[64:67]
	s_setprio 0
	s_setprio 1
	v_mfma_f32_16x16x32_bf16 v[28:31], v[160:163], v[182:185], v[28:31]
	v_mfma_f32_16x16x32_bf16 v[28:31], v[170:173], v[186:189], v[28:31]
	v_mfma_f32_16x16x32_bf16 v[24:27], v[178:181], v[186:189], v[24:27]
	v_mfma_f32_16x16x32_bf16 v[24:27], v[174:177], v[182:185], v[24:27]
	v_mfma_f32_16x16x32_bf16 v[16:19], v[174:177], v[190:193], v[16:19]
	v_mfma_f32_16x16x32_bf16 v[16:19], v[178:181], v[194:197], v[16:19]
	v_mfma_f32_16x16x32_bf16 v[20:23], v[170:173], v[194:197], v[20:23]
	v_mfma_f32_16x16x32_bf16 v[20:23], v[160:163], v[190:193], v[20:23]
	v_mfma_f32_16x16x32_bf16 v[12:15], v[160:163], v[198:201], v[12:15]
	v_mfma_f32_16x16x32_bf16 v[12:15], v[170:173], v[202:205], v[12:15]
	v_mfma_f32_16x16x32_bf16 v[8:11], v[178:181], v[202:205], v[8:11]
	v_mfma_f32_16x16x32_bf16 v[8:11], v[174:177], v[198:201], v[8:11]
	v_mfma_f32_16x16x32_bf16 v[0:3], v[174:177], v[206:209], v[0:3]
	v_mfma_f32_16x16x32_bf16 v[0:3], v[178:181], v[210:213], v[0:3]
	s_setprio 2
	s_barrier
; #define PG8_STAGE(bufoff, gbase, voff) do { _Pragma("unroll") for (int _i = 0; _i < 2; ++_i) \
;         __builtin_amdgcn_global_load_lds((const unsigned*)((const char*)(gbase) + (voff)[_i]), (PG8_LAS unsigned*)(lds + (bufoff) + ldsw + _i * 8192), 16, 0, 0); } while (0)
; #define PG8_LDA(dst, b, h) do { _Pragma("unroll") for (int m = 0; m < 4; ++m) _Pragma("unroll") for (int k = 0; k < 2; ++k) dst[m][k] = *(const PG8_LAS bf16x8*)(lds + PG8_SA(b, h) + aoff + m * 2048 + k * 1024); } while (0)
; #define PG8_LDB(dst, b, h) do { _Pragma("unroll") for (int n = 0; n < 2; ++n) _Pragma("unroll") for (int k = 0; k < 2; ++k) dst[n][k] = *(const PG8_LAS bf16x8*)(lds + PG8_SB(b, h) + boff + n * 2048 + k * 1024); } while (0)
; #define PG8_WAIT_V(n) asm volatile("s_waitcnt vmcnt(" #n ")" ::: "memory")
; #define PG8_WAIT_L(n) asm volatile("s_waitcnt lgkmcnt(" #n ")" ::: "memory")
; #define PG8_BAR __builtin_amdgcn_s_barrier()
; #define PG8_SCHED __builtin_amdgcn_sched_barrier(0)
; template <class Epi, class Sched, bool ALIGN_EPI = false, bool SP2 = false>
; __device__ __forceinline__ void gemm_phase(PG8_LAS unsigned char* lds, const Gemm g, const Sched& S, const Epi& E, int tid_in) {
;     ...
;             PG8_WAIT_V(8); PG8_WAIT_L(0); PG8_BAR; PG8_MMA(1, 0, At, B0); PG8_MMA(1, 1, At, B1); PG8_BAR; PG8_SCHED;
;             PG8_LDB(B0, 1, 0); PG8_LDB(B1, 1, 1); PG8_SCHED; PG8_LDA(At, 1, 0); PG8_STAGE(PG8_SA(0, 1), a2 + hstepA, voffA);
;             PG8_WAIT_V(8); PG8_WAIT_L(0); PG8_BAR; PG8_MMA(0, 0, At, B0); PG8_MMA(0, 1, At, B1); PG8_BAR; PG8_SCHED;
;             PG8_LDA(At, 1, 1); PG8_STAGE(PG8_SB(1, 0), b3, voffB); PG8_STAGE(PG8_SB(1, 1), b3 + hstep, voffB); PG8_STAGE(PG8_SA(1, 0), a3, voffA);
;             PG8_WAIT_V(8); PG8_WAIT_L(0); PG8_BAR; PG8_MMA(1, 0, At, B0); PG8_MMA(1, 1, At, B1); PG8_BAR; PG8_SCHED;
	v_mfma_f32_16x16x32_bf16 v[4:7], v[170:173], v[210:213], v[4:7]
	v_mfma_f32_16x16x32_bf16 v[4:7], v[160:163], v[206:209], v[4:7]
	s_setprio 0
	s_add_i32 s62, 0, 0x18000
	s_add_i32 s63, 0, 0x1c000
	v_add_u32_e32 v156, s62, v165
	v_add_u32_e32 v178, s63, v165
	ds_read_b128 v[128:131], v156
	ds_read_b128 v[132:135], v156 offset:1024
	ds_read_b128 v[152:155], v156 offset:2048
	ds_read_b128 v[156:159], v156 offset:3072
	ds_read_b128 v[160:163], v178
	ds_read_b128 v[170:173], v178 offset:1024
	ds_read_b128 v[174:177], v178 offset:2048
	ds_read_b128 v[178:181], v178 offset:3072
	s_add_u32 s38, s38, 0x100000
	s_addc_u32 s39, s39, 0
	s_mov_b32 m0, s45
	ds_read_b128 v[182:185], v169 offset:32768
	ds_read_b128 v[186:189], v169 offset:33792
	ds_read_b128 v[190:193], v169 offset:34816
	ds_read_b128 v[194:197], v169 offset:35840
	ds_read_b128 v[198:201], v169 offset:36864
	ds_read_b128 v[202:205], v169 offset:37888
	ds_read_b128 v[206:209], v169 offset:38912
	ds_read_b128 v[210:213], v169 offset:39936
	global_load_lds_dwordx4 v136, s[38:39]
	s_mov_b32 m0, s46
	s_nop 0
	global_load_lds_dwordx4 v140, s[38:39]
	s_waitcnt vmcnt(8)
	s_waitcnt lgkmcnt(0)
	s_barrier
	s_setprio 1
	s_waitcnt lgkmcnt(0)
	v_mfma_f32_16x16x32_bf16 v[124:127], v[128:131], v[182:185], v[124:127]
	v_mfma_f32_16x16x32_bf16 v[124:127], v[132:135], v[186:189], v[124:127]
	v_mfma_f32_16x16x32_bf16 v[120:123], v[156:159], v[186:189], v[120:123]
	v_mfma_f32_16x16x32_bf16 v[120:123], v[152:155], v[182:185], v[120:123]
	v_mfma_f32_16x16x32_bf16 v[112:115], v[152:155], v[190:193], v[112:115]
	v_mfma_f32_16x16x32_bf16 v[112:115], v[156:159], v[194:197], v[112:115]
	v_mfma_f32_16x16x32_bf16 v[116:119], v[132:135], v[194:197], v[116:119]
	v_mfma_f32_16x16x32_bf16 v[116:119], v[128:131], v[190:193], v[116:119]
	v_mfma_f32_16x16x32_bf16 v[108:111], v[128:131], v[198:201], v[108:111]
	v_mfma_f32_16x16x32_bf16 v[108:111], v[132:135], v[202:205], v[108:111]
	v_mfma_f32_16x16x32_bf16 v[104:107], v[156:159], v[202:205], v[104:107]
	v_mfma_f32_16x16x32_bf16 v[104:107], v[152:155], v[198:201], v[104:107]
	v_mfma_f32_16x16x32_bf16 v[96:99], v[152:155], v[206:209], v[96:99]
	v_mfma_f32_16x16x32_bf16 v[96:99], v[156:159], v[210:213], v[96:99]
	v_mfma_f32_16x16x32_bf16 v[100:103], v[132:135], v[210:213], v[100:103]
	v_mfma_f32_16x16x32_bf16 v[100:103], v[128:131], v[206:209], v[100:103]
	s_setprio 0
	s_setprio 1
	v_mfma_f32_16x16x32_bf16 v[68:71], v[160:163], v[182:185], v[68:71]
	v_mfma_f32_16x16x32_bf16 v[68:71], v[170:173], v[186:189], v[68:71]
	v_mfma_f32_16x16x32_bf16 v[60:63], v[178:181], v[186:189], v[60:63]
	v_mfma_f32_16x16x32_bf16 v[60:63], v[174:177], v[182:185], v[60:63]
	v_mfma_f32_16x16x32_bf16 v[48:51], v[174:177], v[190:193], v[48:51]
	v_mfma_f32_16x16x32_bf16 v[48:51], v[178:181], v[194:197], v[48:51]
	v_mfma_f32_16x16x32_bf16 v[52:55], v[170:173], v[194:197], v[52:55]
	v_mfma_f32_16x16x32_bf16 v[52:55], v[160:163], v[190:193], v[52:55]
	v_mfma_f32_16x16x32_bf16 v[44:47], v[160:163], v[198:201], v[44:47]
	v_mfma_f32_16x16x32_bf16 v[44:47], v[170:173], v[202:205], v[44:47]
	v_mfma_f32_16x16x32_bf16 v[40:43], v[178:181], v[202:205], v[40:43]
	v_mfma_f32_16x16x32_bf16 v[40:43], v[174:177], v[198:201], v[40:43]
	v_mfma_f32_16x16x32_bf16 v[32:35], v[174:177], v[206:209], v[32:35]
	v_mfma_f32_16x16x32_bf16 v[32:35], v[178:181], v[210:213], v[32:35]
	s_setprio 2
	s_barrier
	v_mfma_f32_16x16x32_bf16 v[36:39], v[170:173], v[210:213], v[36:39]
	v_mfma_f32_16x16x32_bf16 v[36:39], v[160:163], v[206:209], v[36:39]
	s_setprio 0
	s_add_i32 s38, s62, s43
	s_mov_b32 m0, s38
	ds_read_b128 v[182:185], v169 offset:49152
	ds_read_b128 v[186:189], v169 offset:50176
	ds_read_b128 v[190:193], v169 offset:51200
	ds_read_b128 v[194:197], v169 offset:52224
	ds_read_b128 v[198:201], v169 offset:53248
	ds_read_b128 v[202:205], v169 offset:54272
	ds_read_b128 v[206:209], v169 offset:55296
	ds_read_b128 v[210:213], v169 offset:56320
	global_load_lds_dwordx4 v138, s[98:99]
	s_add_i32 m0, s38, 0x2000
	s_add_u32 s36, s36, 0x100080
	s_addc_u32 s37, s37, 0
	s_add_i32 s38, s63, s43
	global_load_lds_dwordx4 v142, s[98:99]
	s_mov_b32 m0, s38
	s_nop 0
	global_load_lds_dwordx4 v138, s[36:37]
	s_add_i32 m0, s38, 0x2000
	s_nop 0
	global_load_lds_dwordx4 v142, s[36:37]
	s_mov_b32 m0, s51
	s_nop 0
	global_load_lds_dwordx4 v136, s[100:101]
	s_mov_b32 m0, s52
	s_nop 0
	global_load_lds_dwordx4 v140, s[100:101]
	s_waitcnt vmcnt(8)
	s_waitcnt lgkmcnt(0)
	s_barrier
	s_setprio 1
	s_waitcnt lgkmcnt(0)
	v_mfma_f32_16x16x32_bf16 v[92:95], v[128:131], v[182:185], v[92:95]
	v_mfma_f32_16x16x32_bf16 v[92:95], v[132:135], v[186:189], v[92:95]
	v_mfma_f32_16x16x32_bf16 v[88:91], v[156:159], v[186:189], v[88:91]
	v_mfma_f32_16x16x32_bf16 v[88:91], v[152:155], v[182:185], v[88:91]
	v_mfma_f32_16x16x32_bf16 v[80:83], v[152:155], v[190:193], v[80:83]
	v_mfma_f32_16x16x32_bf16 v[80:83], v[156:159], v[194:197], v[80:83]
	v_mfma_f32_16x16x32_bf16 v[84:87], v[132:135], v[194:197], v[84:87]
	v_mfma_f32_16x16x32_bf16 v[84:87], v[128:131], v[190:193], v[84:87]
	v_mfma_f32_16x16x32_bf16 v[76:79], v[128:131], v[198:201], v[76:79]
	v_mfma_f32_16x16x32_bf16 v[76:79], v[132:135], v[202:205], v[76:79]
	v_mfma_f32_16x16x32_bf16 v[72:75], v[156:159], v[202:205], v[72:75]
	v_mfma_f32_16x16x32_bf16 v[72:75], v[152:155], v[198:201], v[72:75]
	v_mfma_f32_16x16x32_bf16 v[56:59], v[152:155], v[206:209], v[56:59]
	v_mfma_f32_16x16x32_bf16 v[56:59], v[156:159], v[210:213], v[56:59]
	v_mfma_f32_16x16x32_bf16 v[64:67], v[132:135], v[210:213], v[64:67]
	v_mfma_f32_16x16x32_bf16 v[64:67], v[128:131], v[206:209], v[64:67]
	s_setprio 0
	s_setprio 1
	v_mfma_f32_16x16x32_bf16 v[28:31], v[160:163], v[182:185], v[28:31]
	v_mfma_f32_16x16x32_bf16 v[28:31], v[170:173], v[186:189], v[28:31]
	v_mfma_f32_16x16x32_bf16 v[24:27], v[178:181], v[186:189], v[24:27]
	v_mfma_f32_16x16x32_bf16 v[24:27], v[174:177], v[182:185], v[24:27]
	v_mfma_f32_16x16x32_bf16 v[16:19], v[174:177], v[190:193], v[16:19]
	v_mfma_f32_16x16x32_bf16 v[16:19], v[178:181], v[194:197], v[16:19]
	v_mfma_f32_16x16x32_bf16 v[20:23], v[170:173], v[194:197], v[20:23]
	v_mfma_f32_16x16x32_bf16 v[20:23], v[160:163], v[190:193], v[20:23]
	v_mfma_f32_16x16x32_bf16 v[12:15], v[160:163], v[198:201], v[12:15]
	v_mfma_f32_16x16x32_bf16 v[12:15], v[170:173], v[202:205], v[12:15]
	v_mfma_f32_16x16x32_bf16 v[8:11], v[178:181], v[202:205], v[8:11]
	v_mfma_f32_16x16x32_bf16 v[8:11], v[174:177], v[198:201], v[8:11]
	v_mfma_f32_16x16x32_bf16 v[0:3], v[174:177], v[206:209], v[0:3]
	v_mfma_f32_16x16x32_bf16 v[0:3], v[178:181], v[210:213], v[0:3]
	s_setprio 2
	s_barrier
	v_mfma_f32_16x16x32_bf16 v[4:7], v[170:173], v[210:213], v[4:7]
	v_mfma_f32_16x16x32_bf16 v[4:7], v[160:163], v[206:209], v[4:7]
	s_setprio 0
	s_add_i32 s61, s61, 2
	s_add_u32 s34, s34, 0x100
	s_addc_u32 s35, s35, 0
	s_add_u32 s59, s59, 0x100
	s_addc_u32 s60, s60, 0
	s_cmp_gt_u32 s61, 61
	s_cbranch_scc0 .LBB0_1031
	s_and_b64 vcc, exec, s[10:11]
	s_cbranch_vccz .LBB0_1034
	s_barrier

; #define PG8_STAGE(bufoff, gbase, voff) do { _Pragma("unroll") for (int _i = 0; _i < 2; ++_i) \
;         __builtin_amdgcn_global_load_lds((const unsigned*)((const char*)(gbase) + (voff)[_i]), (PG8_LAS unsigned*)(lds + (bufoff) + ldsw + _i * 8192), 16, 0, 0); } while (0)
; #define PG8_LDA(dst, b, h) do { _Pragma("unroll") for (int m = 0; m < 4; ++m) _Pragma("unroll") for (int k = 0; k < 2; ++k) dst[m][k] = *(const PG8_LAS bf16x8*)(lds + PG8_SA(b, h) + aoff + m * 2048 + k * 1024); } while (0)
; #define PG8_LDB(dst, b, h) do { _Pragma("unroll") for (int n = 0; n < 2; ++n) _Pragma("unroll") for (int k = 0; k < 2; ++k) dst[n][k] = *(const PG8_LAS bf16x8*)(lds + PG8_SB(b, h) + boff + n * 2048 + k * 1024); } while (0)
; #define PG8_WAIT_V(n) asm volatile("s_waitcnt vmcnt(" #n ")" ::: "memory")
; #define PG8_WAIT_L(n) asm volatile("s_waitcnt lgkmcnt(" #n ")" ::: "memory")
; #define PG8_BAR __builtin_amdgcn_s_barrier()
; #define PG8_SCHED __builtin_amdgcn_sched_barrier(0)
; template <class Epi, class Sched, bool ALIGN_EPI = false, bool SP2 = false>
; __device__ __forceinline__ void gemm_phase(PG8_LAS unsigned char* lds, const Gemm g, const Sched& S, const Epi& E, int tid_in) {
;     ...
;         for (int t = 0; t < nt; t += 2) {
;             const bool last = (t == nt - 2);
;             const char* a1 = cA + (size_t)(t + 1) * kstep;
;             const char* a2 = last ? nA : cA + (size_t)(t + 2) * kstep; const char* b2 = last ? nB : cB + (size_t)(t + 2) * kstep;
;             const char* a3 = a2 + kstep; const char* b3 = b2 + kstep;
;             if (last && has_next) S.a_ready(nxt);
;             if constexpr (SP2) {
;             PG8_LDB(B0, 0, 0); PG8_LDB(B1, 0, 1); PG8_SCHED; PG8_LDA(At, 0, 0); PG8_STAGE(PG8_SA(1, 1), a1 + hstepA, voffA);
;             PG8_WAIT_V(8); PG8_WAIT_L(0); PG8_BAR; PG8_MMA(0, 0, At, B0); PG8_MMA(0, 1, At, B1); PG8_BAR; PG8_SCHED;
;             PG8_LDA(At, 0, 1); PG8_STAGE(PG8_SB(0, 0), b2, voffB); PG8_STAGE(PG8_SB(0, 1), b2 + hstep, voffB); PG8_STAGE(PG8_SA(0, 0), a2, voffA);
;             PG8_WAIT_V(8); PG8_WAIT_L(0); PG8_BAR; PG8_MMA(1, 0, At, B0); PG8_MMA(1, 1, At, B1); PG8_BAR; PG8_SCHED;
.LBB0_1162:
	ds_read_b128 v[128:131], v192
	ds_read_b128 v[132:135], v192 offset:1024
	ds_read_b128 v[136:139], v192 offset:2048
	ds_read_b128 v[140:143], v192 offset:3072
	ds_read_b128 v[160:163], v193
	ds_read_b128 v[164:167], v193 offset:1024
	ds_read_b128 v[168:171], v193 offset:2048
	ds_read_b128 v[172:175], v193 offset:3072
	s_add_u32 s38, s36, 0x100
	s_addc_u32 s39, s37, 0
	s_cmp_eq_u32 s69, 60
	s_cselect_b32 s43, s27, s39
	s_cselect_b32 s42, s35, s38
	s_cselect_b32 s41, s25, s68
	s_cselect_b32 s40, s66, s67
	s_add_i32 m0, s52, 0xc000
	ds_read_b128 v[176:179], v194
	ds_read_b128 v[180:183], v194 offset:1024
	ds_read_b128 v[184:187], v194 offset:2048
	ds_read_b128 v[196:199], v194 offset:3072
	ds_read_b128 v[200:203], v194 offset:4096
	ds_read_b128 v[204:207], v194 offset:5120
	ds_read_b128 v[208:211], v194 offset:6144
	ds_read_b128 v[212:215], v194 offset:7168
	global_load_lds_dwordx4 v152, s[36:37]
	s_add_i32 m0, s52, 0xe000
	s_nop 0
	global_load_lds_dwordx4 v154, s[36:37]
	s_waitcnt vmcnt(8)
	s_waitcnt lgkmcnt(0)
	s_barrier
	s_setprio 1
	s_waitcnt lgkmcnt(0)
	v_mfma_f32_16x16x32_bf16 v[92:95], v[128:131], v[176:179], v[92:95]
	v_mfma_f32_16x16x32_bf16 v[92:95], v[132:135], v[180:183], v[92:95]
	v_mfma_f32_16x16x32_bf16 v[28:31], v[140:143], v[180:183], v[28:31]
	v_mfma_f32_16x16x32_bf16 v[28:31], v[136:139], v[176:179], v[28:31]
	v_mfma_f32_16x16x32_bf16 v[24:27], v[136:139], v[184:187], v[24:27]
	v_mfma_f32_16x16x32_bf16 v[24:27], v[140:143], v[196:199], v[24:27]
	v_mfma_f32_16x16x32_bf16 v[88:91], v[132:135], v[196:199], v[88:91]
	v_mfma_f32_16x16x32_bf16 v[88:91], v[128:131], v[184:187], v[88:91]
	v_mfma_f32_16x16x32_bf16 v[116:119], v[128:131], v[200:203], v[116:119]
	v_mfma_f32_16x16x32_bf16 v[116:119], v[132:135], v[204:207], v[116:119]
	v_mfma_f32_16x16x32_bf16 v[52:55], v[140:143], v[204:207], v[52:55]
	v_mfma_f32_16x16x32_bf16 v[52:55], v[136:139], v[200:203], v[52:55]
	v_mfma_f32_16x16x32_bf16 v[44:47], v[136:139], v[208:211], v[44:47]
	v_mfma_f32_16x16x32_bf16 v[44:47], v[140:143], v[212:215], v[44:47]
	v_mfma_f32_16x16x32_bf16 v[108:111], v[132:135], v[212:215], v[108:111]
	v_mfma_f32_16x16x32_bf16 v[108:111], v[128:131], v[208:211], v[108:111]
	s_setprio 0
	s_setprio 1
	v_mfma_f32_16x16x32_bf16 v[84:87], v[160:163], v[176:179], v[84:87]
	v_mfma_f32_16x16x32_bf16 v[84:87], v[164:167], v[180:183], v[84:87]
	v_mfma_f32_16x16x32_bf16 v[20:23], v[172:175], v[180:183], v[20:23]
	v_mfma_f32_16x16x32_bf16 v[20:23], v[168:171], v[176:179], v[20:23]
	v_mfma_f32_16x16x32_bf16 v[0:3], v[168:171], v[184:187], v[0:3]
	v_mfma_f32_16x16x32_bf16 v[0:3], v[172:175], v[196:199], v[0:3]
	v_mfma_f32_16x16x32_bf16 v[64:67], v[164:167], v[196:199], v[64:67]
	v_mfma_f32_16x16x32_bf16 v[64:67], v[160:163], v[184:187], v[64:67]
	v_mfma_f32_16x16x32_bf16 v[124:127], v[160:163], v[200:203], v[124:127]
	v_mfma_f32_16x16x32_bf16 v[124:127], v[164:167], v[204:207], v[124:127]
	v_mfma_f32_16x16x32_bf16 v[60:63], v[172:175], v[204:207], v[60:63]
	v_mfma_f32_16x16x32_bf16 v[60:63], v[168:171], v[200:203], v[60:63]
	v_mfma_f32_16x16x32_bf16 v[56:59], v[168:171], v[208:211], v[56:59]
	v_mfma_f32_16x16x32_bf16 v[56:59], v[172:175], v[212:215], v[56:59]
	s_setprio 2
	s_barrier
	v_mfma_f32_16x16x32_bf16 v[120:123], v[164:167], v[212:215], v[120:123]
	v_mfma_f32_16x16x32_bf16 v[120:123], v[160:163], v[208:211], v[120:123]
	s_setprio 0
	s_add_u32 s98, s40, 0x80
	s_addc_u32 s99, s41, 0
	s_add_u32 s100, s42, 0x80
	s_addc_u32 s101, s43, 0
	s_add_i32 s36, s62, s49
	s_mov_b32 m0, s36
	ds_read_b128 v[176:179], v194 offset:16384
	ds_read_b128 v[180:183], v194 offset:17408
	ds_read_b128 v[184:187], v194 offset:18432
	ds_read_b128 v[196:199], v194 offset:19456
	ds_read_b128 v[200:203], v194 offset:20480
	ds_read_b128 v[204:207], v194 offset:21504
	ds_read_b128 v[208:211], v194 offset:22528
	ds_read_b128 v[212:215], v194 offset:23552
	global_load_lds_dwordx4 v148, s[40:41]
	s_add_i32 m0, s36, 0x2000
	s_add_u32 s36, s40, 0x100000
	s_addc_u32 s37, s41, 0
	s_add_i32 s70, s63, s49
	global_load_lds_dwordx4 v144, s[40:41]
	s_mov_b32 m0, s70
	s_nop 0
	global_load_lds_dwordx4 v148, s[36:37]
	s_add_i32 m0, s70, 0x2000
	s_nop 0
	global_load_lds_dwordx4 v144, s[36:37]
	s_mov_b32 m0, s52
	s_nop 0
	global_load_lds_dwordx4 v150, s[42:43]
	s_mov_b32 m0, s53
	s_nop 0
	global_load_lds_dwordx4 v146, s[42:43]
	s_waitcnt vmcnt(8)
	s_waitcnt lgkmcnt(0)
	s_barrier
	s_setprio 1
	s_waitcnt lgkmcnt(0)
	v_mfma_f32_16x16x32_bf16 v[100:103], v[128:131], v[176:179], v[100:103]
	v_mfma_f32_16x16x32_bf16 v[100:103], v[132:135], v[180:183], v[100:103]
	v_mfma_f32_16x16x32_bf16 v[36:39], v[140:143], v[180:183], v[36:39]
	v_mfma_f32_16x16x32_bf16 v[36:39], v[136:139], v[176:179], v[36:39]
	v_mfma_f32_16x16x32_bf16 v[32:35], v[136:139], v[184:187], v[32:35]
	v_mfma_f32_16x16x32_bf16 v[32:35], v[140:143], v[196:199], v[32:35]
	v_mfma_f32_16x16x32_bf16 v[96:99], v[132:135], v[196:199], v[96:99]
	v_mfma_f32_16x16x32_bf16 v[96:99], v[128:131], v[184:187], v[96:99]
	v_mfma_f32_16x16x32_bf16 v[80:83], v[128:131], v[200:203], v[80:83]
	v_mfma_f32_16x16x32_bf16 v[80:83], v[132:135], v[204:207], v[80:83]
	v_mfma_f32_16x16x32_bf16 v[16:19], v[140:143], v[204:207], v[16:19]
	v_mfma_f32_16x16x32_bf16 v[16:19], v[136:139], v[200:203], v[16:19]
	v_mfma_f32_16x16x32_bf16 v[12:15], v[136:139], v[208:211], v[12:15]
	v_mfma_f32_16x16x32_bf16 v[12:15], v[140:143], v[212:215], v[12:15]
	v_mfma_f32_16x16x32_bf16 v[76:79], v[132:135], v[212:215], v[76:79]
	v_mfma_f32_16x16x32_bf16 v[76:79], v[128:131], v[208:211], v[76:79]
	s_setprio 0
	s_setprio 1
	v_mfma_f32_16x16x32_bf16 v[112:115], v[160:163], v[176:179], v[112:115]
	v_mfma_f32_16x16x32_bf16 v[112:115], v[164:167], v[180:183], v[112:115]
	v_mfma_f32_16x16x32_bf16 v[48:51], v[172:175], v[180:183], v[48:51]
	v_mfma_f32_16x16x32_bf16 v[48:51], v[168:171], v[176:179], v[48:51]
	v_mfma_f32_16x16x32_bf16 v[40:43], v[168:171], v[184:187], v[40:43]
	v_mfma_f32_16x16x32_bf16 v[40:43], v[172:175], v[196:199], v[40:43]
	v_mfma_f32_16x16x32_bf16 v[104:107], v[164:167], v[196:199], v[104:107]
	v_mfma_f32_16x16x32_bf16 v[104:107], v[160:163], v[184:187], v[104:107]
	v_mfma_f32_16x16x32_bf16 v[72:75], v[160:163], v[200:203], v[72:75]
	v_mfma_f32_16x16x32_bf16 v[72:75], v[164:167], v[204:207], v[72:75]
	v_mfma_f32_16x16x32_bf16 v[8:11], v[172:175], v[204:207], v[8:11]
	v_mfma_f32_16x16x32_bf16 v[8:11], v[168:171], v[200:203], v[8:11]
	v_mfma_f32_16x16x32_bf16 v[4:7], v[168:171], v[208:211], v[4:7]
	v_mfma_f32_16x16x32_bf16 v[4:7], v[172:175], v[212:215], v[4:7]
	s_setprio 2
	s_barrier
; #define PG8_STAGE(bufoff, gbase, voff) do { _Pragma("unroll") for (int _i = 0; _i < 2; ++_i) \
;         __builtin_amdgcn_global_load_lds((const unsigned*)((const char*)(gbase) + (voff)[_i]), (PG8_LAS unsigned*)(lds + (bufoff) + ldsw + _i * 8192), 16, 0, 0); } while (0)
; #define PG8_LDA(dst, b, h) do { _Pragma("unroll") for (int m = 0; m < 4; ++m) _Pragma("unroll") for (int k = 0; k < 2; ++k) dst[m][k] = *(const PG8_LAS bf16x8*)(lds + PG8_SA(b, h) + aoff + m * 2048 + k * 1024); } while (0)
; #define PG8_LDB(dst, b, h) do { _Pragma("unroll") for (int n = 0; n < 2; ++n) _Pragma("unroll") for (int k = 0; k < 2; ++k) dst[n][k] = *(const PG8_LAS bf16x8*)(lds + PG8_SB(b, h) + boff + n * 2048 + k * 1024); } while (0)
; #define PG8_WAIT_V(n) asm volatile("s_waitcnt vmcnt(" #n ")" ::: "memory")
; #define PG8_WAIT_L(n) asm volatile("s_waitcnt lgkmcnt(" #n ")" ::: "memory")
; #define PG8_BAR __builtin_amdgcn_s_barrier()
; #define PG8_SCHED __builtin_amdgcn_sched_barrier(0)
; template <class Epi, class Sched, bool ALIGN_EPI = false, bool SP2 = false>
; __device__ __forceinline__ void gemm_phase(PG8_LAS unsigned char* lds, const Gemm g, const Sched& S, const Epi& E, int tid_in) {
;     ...
;             PG8_WAIT_V(8); PG8_WAIT_L(0); PG8_BAR; PG8_MMA(1, 0, At, B0); PG8_MMA(1, 1, At, B1); PG8_BAR; PG8_SCHED;
;             PG8_LDB(B0, 1, 0); PG8_LDB(B1, 1, 1); PG8_SCHED; PG8_LDA(At, 1, 0); PG8_STAGE(PG8_SA(0, 1), a2 + hstepA, voffA);
;             PG8_WAIT_V(8); PG8_WAIT_L(0); PG8_BAR; PG8_MMA(0, 0, At, B0); PG8_MMA(0, 1, At, B1); PG8_BAR; PG8_SCHED;
;             PG8_LDA(At, 1, 1); PG8_STAGE(PG8_SB(1, 0), b3, voffB); PG8_STAGE(PG8_SB(1, 1), b3 + hstep, voffB); PG8_STAGE(PG8_SA(1, 0), a3, voffA);
;             PG8_WAIT_V(8); PG8_WAIT_L(0); PG8_BAR; PG8_MMA(1, 0, At, B0); PG8_MMA(1, 1, At, B1); PG8_BAR; PG8_SCHED;
	v_mfma_f32_16x16x32_bf16 v[68:71], v[164:167], v[212:215], v[68:71]
	v_mfma_f32_16x16x32_bf16 v[68:71], v[160:163], v[208:211], v[68:71]
	s_setprio 0
	s_add_i32 s70, 0, 0x18000
	s_add_i32 s71, 0, 0x1c000
	v_add_u32_e32 v140, s70, v189
	v_add_u32_e32 v172, s71, v189
	ds_read_b128 v[128:131], v140
	ds_read_b128 v[132:135], v140 offset:1024
	ds_read_b128 v[136:139], v140 offset:2048
	ds_read_b128 v[140:143], v140 offset:3072
	ds_read_b128 v[160:163], v172
	ds_read_b128 v[164:167], v172 offset:1024
	ds_read_b128 v[168:171], v172 offset:2048
	ds_read_b128 v[172:175], v172 offset:3072
	s_add_u32 s36, s42, 0x8000
	s_addc_u32 s37, s43, 0
	s_mov_b32 m0, s54
	ds_read_b128 v[176:179], v194 offset:32768
	ds_read_b128 v[180:183], v194 offset:33792
	ds_read_b128 v[184:187], v194 offset:34816
	ds_read_b128 v[196:199], v194 offset:35840
	ds_read_b128 v[200:203], v194 offset:36864
	ds_read_b128 v[204:207], v194 offset:37888
	ds_read_b128 v[208:211], v194 offset:38912
	ds_read_b128 v[212:215], v194 offset:39936
	global_load_lds_dwordx4 v150, s[36:37]
	s_mov_b32 m0, s55
	s_nop 0
	global_load_lds_dwordx4 v146, s[36:37]
	s_waitcnt vmcnt(8)
	s_waitcnt lgkmcnt(0)
	s_barrier
	s_setprio 1
	s_waitcnt lgkmcnt(0)
	v_mfma_f32_16x16x32_bf16 v[92:95], v[128:131], v[176:179], v[92:95]
	v_mfma_f32_16x16x32_bf16 v[92:95], v[132:135], v[180:183], v[92:95]
	v_mfma_f32_16x16x32_bf16 v[28:31], v[140:143], v[180:183], v[28:31]
	v_mfma_f32_16x16x32_bf16 v[28:31], v[136:139], v[176:179], v[28:31]
	v_mfma_f32_16x16x32_bf16 v[24:27], v[136:139], v[184:187], v[24:27]
	v_mfma_f32_16x16x32_bf16 v[24:27], v[140:143], v[196:199], v[24:27]
	v_mfma_f32_16x16x32_bf16 v[88:91], v[132:135], v[196:199], v[88:91]
	v_mfma_f32_16x16x32_bf16 v[88:91], v[128:131], v[184:187], v[88:91]
	v_mfma_f32_16x16x32_bf16 v[116:119], v[128:131], v[200:203], v[116:119]
	v_mfma_f32_16x16x32_bf16 v[116:119], v[132:135], v[204:207], v[116:119]
	v_mfma_f32_16x16x32_bf16 v[52:55], v[140:143], v[204:207], v[52:55]
	v_mfma_f32_16x16x32_bf16 v[52:55], v[136:139], v[200:203], v[52:55]
	v_mfma_f32_16x16x32_bf16 v[44:47], v[136:139], v[208:211], v[44:47]
	v_mfma_f32_16x16x32_bf16 v[44:47], v[140:143], v[212:215], v[44:47]
	v_mfma_f32_16x16x32_bf16 v[108:111], v[132:135], v[212:215], v[108:111]
	v_mfma_f32_16x16x32_bf16 v[108:111], v[128:131], v[208:211], v[108:111]
	s_setprio 0
	s_setprio 1
	v_mfma_f32_16x16x32_bf16 v[84:87], v[160:163], v[176:179], v[84:87]
	v_mfma_f32_16x16x32_bf16 v[84:87], v[164:167], v[180:183], v[84:87]
	v_mfma_f32_16x16x32_bf16 v[20:23], v[172:175], v[180:183], v[20:23]
	v_mfma_f32_16x16x32_bf16 v[20:23], v[168:171], v[176:179], v[20:23]
	v_mfma_f32_16x16x32_bf16 v[0:3], v[168:171], v[184:187], v[0:3]
	v_mfma_f32_16x16x32_bf16 v[0:3], v[172:175], v[196:199], v[0:3]
	v_mfma_f32_16x16x32_bf16 v[64:67], v[164:167], v[196:199], v[64:67]
	v_mfma_f32_16x16x32_bf16 v[64:67], v[160:163], v[184:187], v[64:67]
	v_mfma_f32_16x16x32_bf16 v[124:127], v[160:163], v[200:203], v[124:127]
	v_mfma_f32_16x16x32_bf16 v[124:127], v[164:167], v[204:207], v[124:127]
	v_mfma_f32_16x16x32_bf16 v[60:63], v[172:175], v[204:207], v[60:63]
	v_mfma_f32_16x16x32_bf16 v[60:63], v[168:171], v[200:203], v[60:63]
	v_mfma_f32_16x16x32_bf16 v[56:59], v[168:171], v[208:211], v[56:59]
	v_mfma_f32_16x16x32_bf16 v[56:59], v[172:175], v[212:215], v[56:59]
	s_setprio 2
	s_barrier
	v_mfma_f32_16x16x32_bf16 v[120:123], v[164:167], v[212:215], v[120:123]
	v_mfma_f32_16x16x32_bf16 v[120:123], v[160:163], v[208:211], v[120:123]
	s_setprio 0
	s_add_i32 s36, s70, s49
	s_mov_b32 m0, s36
	ds_read_b128 v[176:179], v194 offset:49152
	ds_read_b128 v[180:183], v194 offset:50176
	ds_read_b128 v[184:187], v194 offset:51200
	ds_read_b128 v[196:199], v194 offset:52224
	ds_read_b128 v[200:203], v194 offset:53248
	ds_read_b128 v[204:207], v194 offset:54272
	ds_read_b128 v[208:211], v194 offset:55296
	ds_read_b128 v[212:215], v194 offset:56320
	global_load_lds_dwordx4 v148, s[98:99]
	s_add_i32 m0, s36, 0x2000
	s_add_u32 s36, s40, 0x100080
	s_addc_u32 s37, s41, 0
	s_add_i32 s40, s71, s49
	global_load_lds_dwordx4 v144, s[98:99]
	s_mov_b32 m0, s40
	s_nop 0
	global_load_lds_dwordx4 v148, s[36:37]
	s_add_i32 m0, s40, 0x2000
	s_nop 0
	global_load_lds_dwordx4 v144, s[36:37]
	s_mov_b32 m0, s59
	s_nop 0
	global_load_lds_dwordx4 v150, s[100:101]
	s_mov_b32 m0, s60
	s_nop 0
	global_load_lds_dwordx4 v146, s[100:101]
	s_waitcnt vmcnt(8)
	s_waitcnt lgkmcnt(0)
	s_barrier
	s_setprio 1
	s_waitcnt lgkmcnt(0)
	v_mfma_f32_16x16x32_bf16 v[100:103], v[128:131], v[176:179], v[100:103]
	v_mfma_f32_16x16x32_bf16 v[100:103], v[132:135], v[180:183], v[100:103]
	v_mfma_f32_16x16x32_bf16 v[36:39], v[140:143], v[180:183], v[36:39]
	v_mfma_f32_16x16x32_bf16 v[36:39], v[136:139], v[176:179], v[36:39]
	v_mfma_f32_16x16x32_bf16 v[32:35], v[136:139], v[184:187], v[32:35]
	v_mfma_f32_16x16x32_bf16 v[32:35], v[140:143], v[196:199], v[32:35]
	v_mfma_f32_16x16x32_bf16 v[96:99], v[132:135], v[196:199], v[96:99]
	v_mfma_f32_16x16x32_bf16 v[96:99], v[128:131], v[184:187], v[96:99]
	v_mfma_f32_16x16x32_bf16 v[80:83], v[128:131], v[200:203], v[80:83]
	v_mfma_f32_16x16x32_bf16 v[80:83], v[132:135], v[204:207], v[80:83]
	v_mfma_f32_16x16x32_bf16 v[16:19], v[140:143], v[204:207], v[16:19]
	v_mfma_f32_16x16x32_bf16 v[16:19], v[136:139], v[200:203], v[16:19]
	v_mfma_f32_16x16x32_bf16 v[12:15], v[136:139], v[208:211], v[12:15]
	v_mfma_f32_16x16x32_bf16 v[12:15], v[140:143], v[212:215], v[12:15]
	v_mfma_f32_16x16x32_bf16 v[76:79], v[132:135], v[212:215], v[76:79]
	v_mfma_f32_16x16x32_bf16 v[76:79], v[128:131], v[208:211], v[76:79]
	s_setprio 0
	s_setprio 1
	v_mfma_f32_16x16x32_bf16 v[112:115], v[160:163], v[176:179], v[112:115]
	v_mfma_f32_16x16x32_bf16 v[112:115], v[164:167], v[180:183], v[112:115]
	v_mfma_f32_16x16x32_bf16 v[48:51], v[172:175], v[180:183], v[48:51]
	v_mfma_f32_16x16x32_bf16 v[48:51], v[168:171], v[176:179], v[48:51]
	v_mfma_f32_16x16x32_bf16 v[40:43], v[168:171], v[184:187], v[40:43]
	v_mfma_f32_16x16x32_bf16 v[40:43], v[172:175], v[196:199], v[40:43]
	v_mfma_f32_16x16x32_bf16 v[104:107], v[164:167], v[196:199], v[104:107]
	v_mfma_f32_16x16x32_bf16 v[104:107], v[160:163], v[184:187], v[104:107]
	v_mfma_f32_16x16x32_bf16 v[72:75], v[160:163], v[200:203], v[72:75]
	v_mfma_f32_16x16x32_bf16 v[72:75], v[164:167], v[204:207], v[72:75]
	v_mfma_f32_16x16x32_bf16 v[8:11], v[172:175], v[204:207], v[8:11]
	v_mfma_f32_16x16x32_bf16 v[8:11], v[168:171], v[200:203], v[8:11]
	v_mfma_f32_16x16x32_bf16 v[4:7], v[168:171], v[208:211], v[4:7]
	v_mfma_f32_16x16x32_bf16 v[4:7], v[172:175], v[212:215], v[4:7]
	s_setprio 2
	s_barrier
	v_mfma_f32_16x16x32_bf16 v[68:71], v[164:167], v[212:215], v[68:71]
	v_mfma_f32_16x16x32_bf16 v[68:71], v[160:163], v[208:211], v[68:71]
	s_setprio 0
	s_add_i32 s69, s69, 2
	s_add_u32 s67, s67, 0x100
	s_addc_u32 s68, s68, 0
	s_cmp_gt_u32 s69, 61
	s_mov_b64 s[36:37], s[38:39]
	s_cbranch_scc0 .LBB0_1162
	s_and_b64 vcc, exec, s[10:11]
	s_cbranch_vccz .LBB0_1165
	s_barrier

; #define PG8_STAGE(bufoff, gbase, voff) do { _Pragma("unroll") for (int _i = 0; _i < 2; ++_i) \
;         __builtin_amdgcn_global_load_lds((const unsigned*)((const char*)(gbase) + (voff)[_i]), (PG8_LAS unsigned*)(lds + (bufoff) + ldsw + _i * 8192), 16, 0, 0); } while (0)
; #define PG8_LDA(dst, b, h) do { _Pragma("unroll") for (int m = 0; m < 4; ++m) _Pragma("unroll") for (int k = 0; k < 2; ++k) dst[m][k] = *(const PG8_LAS bf16x8*)(lds + PG8_SA(b, h) + aoff + m * 2048 + k * 1024); } while (0)
; #define PG8_LDB(dst, b, h) do { _Pragma("unroll") for (int n = 0; n < 2; ++n) _Pragma("unroll") for (int k = 0; k < 2; ++k) dst[n][k] = *(const PG8_LAS bf16x8*)(lds + PG8_SB(b, h) + boff + n * 2048 + k * 1024); } while (0)
; #define PG8_WAIT_V(n) asm volatile("s_waitcnt vmcnt(" #n ")" ::: "memory")
; #define PG8_WAIT_L(n) asm volatile("s_waitcnt lgkmcnt(" #n ")" ::: "memory")
; #define PG8_BAR __builtin_amdgcn_s_barrier()
; #define PG8_SCHED __builtin_amdgcn_sched_barrier(0)
; template <class Epi, class Sched, bool ALIGN_EPI = false, bool SP2 = false>
; __device__ __forceinline__ void gemm_phase(PG8_LAS unsigned char* lds, const Gemm g, const Sched& S, const Epi& E, int tid_in) {
;     ...
;         for (int t = 0; t < nt; t += 2) {
;             const bool last = (t == nt - 2);
;             const char* a1 = cA + (size_t)(t + 1) * kstep;
;             const char* a2 = last ? nA : cA + (size_t)(t + 2) * kstep; const char* b2 = last ? nB : cB + (size_t)(t + 2) * kstep;
;             const char* a3 = a2 + kstep; const char* b3 = b2 + kstep;
;             if (last && has_next) S.a_ready(nxt);
;             if constexpr (SP2) {
;             PG8_LDB(B0, 0, 0); PG8_LDB(B1, 0, 1); PG8_SCHED; PG8_LDA(At, 0, 0); PG8_STAGE(PG8_SA(1, 1), a1 + hstepA, voffA);
;             PG8_WAIT_V(8); PG8_WAIT_L(0); PG8_BAR; PG8_MMA(0, 0, At, B0); PG8_MMA(0, 1, At, B1); PG8_BAR; PG8_SCHED;
;             PG8_LDA(At, 0, 1); PG8_STAGE(PG8_SB(0, 0), b2, voffB); PG8_STAGE(PG8_SB(0, 1), b2 + hstep, voffB); PG8_STAGE(PG8_SA(0, 0), a2, voffA);
;             PG8_WAIT_V(8); PG8_WAIT_L(0); PG8_BAR; PG8_MMA(1, 0, At, B0); PG8_MMA(1, 1, At, B1); PG8_BAR; PG8_SCHED;
;             PG8_LDB(B0, 1, 0); PG8_LDB(B1, 1, 1); PG8_SCHED; PG8_LDA(At, 1, 0); PG8_STAGE(PG8_SA(0, 1), a2 + hstepA, voffA);
;             PG8_WAIT_V(8); PG8_WAIT_L(0); PG8_BAR; PG8_MMA(0, 0, At, B0); PG8_MMA(0, 1, At, B1); PG8_BAR; PG8_SCHED;
.LBB0_1328:
	ds_read_b128 v[128:131], v191
	ds_read_b128 v[132:135], v191 offset:1024
	ds_read_b128 v[152:155], v191 offset:2048
	ds_read_b128 v[156:159], v191 offset:3072
	ds_read_b128 v[160:163], v192
	ds_read_b128 v[164:167], v192 offset:1024
	ds_read_b128 v[168:171], v192 offset:2048
	ds_read_b128 v[172:175], v192 offset:3072
	s_add_u32 s22, s20, 0x100
	s_addc_u32 s23, s21, 0
	s_cmpk_eq_i32 s53, 0xa8
	s_cselect_b32 s27, s5, s23
	s_cselect_b32 s26, s4, s22
	s_cselect_b32 s25, s19, s52
	s_cselect_b32 s24, s18, s51
	s_add_i32 m0, s34, 0xc000
	ds_read_b128 v[176:179], v193
	ds_read_b128 v[180:183], v193 offset:1024
	ds_read_b128 v[184:187], v193 offset:2048
	ds_read_b128 v[194:197], v193 offset:3072
	ds_read_b128 v[198:201], v193 offset:4096
	ds_read_b128 v[202:205], v193 offset:5120
	ds_read_b128 v[206:209], v193 offset:6144
	ds_read_b128 v[210:213], v193 offset:7168
	global_load_lds_dwordx4 v144, s[20:21]
	s_add_i32 m0, s34, 0xe000
	s_nop 0
	global_load_lds_dwordx4 v146, s[20:21]
	s_waitcnt vmcnt(8)
	s_waitcnt lgkmcnt(0)
	s_barrier
	s_setprio 1
	s_waitcnt lgkmcnt(0)
	v_mfma_f32_16x16x32_bf16 v[124:127], v[128:131], v[176:179], v[124:127]
	v_mfma_f32_16x16x32_bf16 v[124:127], v[132:135], v[180:183], v[124:127]
	v_mfma_f32_16x16x32_bf16 v[120:123], v[156:159], v[180:183], v[120:123]
	v_mfma_f32_16x16x32_bf16 v[120:123], v[152:155], v[176:179], v[120:123]
	v_mfma_f32_16x16x32_bf16 v[112:115], v[152:155], v[184:187], v[112:115]
	v_mfma_f32_16x16x32_bf16 v[112:115], v[156:159], v[194:197], v[112:115]
	v_mfma_f32_16x16x32_bf16 v[116:119], v[132:135], v[194:197], v[116:119]
	v_mfma_f32_16x16x32_bf16 v[116:119], v[128:131], v[184:187], v[116:119]
	v_mfma_f32_16x16x32_bf16 v[108:111], v[128:131], v[198:201], v[108:111]
	v_mfma_f32_16x16x32_bf16 v[108:111], v[132:135], v[202:205], v[108:111]
	v_mfma_f32_16x16x32_bf16 v[104:107], v[156:159], v[202:205], v[104:107]
	v_mfma_f32_16x16x32_bf16 v[104:107], v[152:155], v[198:201], v[104:107]
	v_mfma_f32_16x16x32_bf16 v[96:99], v[152:155], v[206:209], v[96:99]
	v_mfma_f32_16x16x32_bf16 v[96:99], v[156:159], v[210:213], v[96:99]
	v_mfma_f32_16x16x32_bf16 v[100:103], v[132:135], v[210:213], v[100:103]
	v_mfma_f32_16x16x32_bf16 v[100:103], v[128:131], v[206:209], v[100:103]
	s_setprio 0
	s_setprio 1
	v_mfma_f32_16x16x32_bf16 v[60:63], v[160:163], v[176:179], v[60:63]
	v_mfma_f32_16x16x32_bf16 v[60:63], v[164:167], v[180:183], v[60:63]
	v_mfma_f32_16x16x32_bf16 v[56:59], v[172:175], v[180:183], v[56:59]
	v_mfma_f32_16x16x32_bf16 v[56:59], v[168:171], v[176:179], v[56:59]
	v_mfma_f32_16x16x32_bf16 v[48:51], v[168:171], v[184:187], v[48:51]
	v_mfma_f32_16x16x32_bf16 v[48:51], v[172:175], v[194:197], v[48:51]
	v_mfma_f32_16x16x32_bf16 v[52:55], v[164:167], v[194:197], v[52:55]
	v_mfma_f32_16x16x32_bf16 v[52:55], v[160:163], v[184:187], v[52:55]
	v_mfma_f32_16x16x32_bf16 v[44:47], v[160:163], v[198:201], v[44:47]
	v_mfma_f32_16x16x32_bf16 v[44:47], v[164:167], v[202:205], v[44:47]
	v_mfma_f32_16x16x32_bf16 v[40:43], v[172:175], v[202:205], v[40:43]
	v_mfma_f32_16x16x32_bf16 v[40:43], v[168:171], v[198:201], v[40:43]
	v_mfma_f32_16x16x32_bf16 v[32:35], v[168:171], v[206:209], v[32:35]
	v_mfma_f32_16x16x32_bf16 v[32:35], v[172:175], v[210:213], v[32:35]
	s_setprio 2
	s_barrier
	v_mfma_f32_16x16x32_bf16 v[36:39], v[164:167], v[210:213], v[36:39]
	v_mfma_f32_16x16x32_bf16 v[36:39], v[160:163], v[206:209], v[36:39]
	s_setprio 0
	s_add_u32 s98, s24, 0x80
	s_addc_u32 s99, s25, 0
	s_add_u32 s100, s26, 0x80
	s_addc_u32 s101, s27, 0
	s_add_i32 s20, s45, s33
	s_mov_b32 m0, s20
	ds_read_b128 v[176:179], v193 offset:16384
	ds_read_b128 v[180:183], v193 offset:17408
	ds_read_b128 v[184:187], v193 offset:18432
	ds_read_b128 v[194:197], v193 offset:19456
	ds_read_b128 v[198:201], v193 offset:20480
	ds_read_b128 v[202:205], v193 offset:21504
	ds_read_b128 v[206:209], v193 offset:22528
	ds_read_b128 v[210:213], v193 offset:23552
	global_load_lds_dwordx4 v138, s[24:25]
	s_add_i32 m0, s20, 0x2000
	s_add_u32 s20, s24, 0x2b0000
	s_addc_u32 s21, s25, 0
	s_add_i32 s54, s46, s33
	global_load_lds_dwordx4 v142, s[24:25]
	s_mov_b32 m0, s54
	s_nop 0
	global_load_lds_dwordx4 v138, s[20:21]
	s_add_i32 m0, s54, 0x2000
	s_nop 0
	global_load_lds_dwordx4 v142, s[20:21]
	s_mov_b32 m0, s34
	s_nop 0
	global_load_lds_dwordx4 v136, s[26:27]
	s_mov_b32 m0, s35
	s_nop 0
	global_load_lds_dwordx4 v140, s[26:27]
	s_waitcnt vmcnt(8)
	s_waitcnt lgkmcnt(0)
	s_barrier
	s_setprio 1
	s_waitcnt lgkmcnt(0)
	v_mfma_f32_16x16x32_bf16 v[92:95], v[128:131], v[176:179], v[92:95]
	v_mfma_f32_16x16x32_bf16 v[92:95], v[132:135], v[180:183], v[92:95]
	v_mfma_f32_16x16x32_bf16 v[88:91], v[156:159], v[180:183], v[88:91]
	v_mfma_f32_16x16x32_bf16 v[88:91], v[152:155], v[176:179], v[88:91]
	v_mfma_f32_16x16x32_bf16 v[80:83], v[152:155], v[184:187], v[80:83]
	v_mfma_f32_16x16x32_bf16 v[80:83], v[156:159], v[194:197], v[80:83]
	v_mfma_f32_16x16x32_bf16 v[84:87], v[132:135], v[194:197], v[84:87]
	v_mfma_f32_16x16x32_bf16 v[84:87], v[128:131], v[184:187], v[84:87]
	v_mfma_f32_16x16x32_bf16 v[76:79], v[128:131], v[198:201], v[76:79]
	v_mfma_f32_16x16x32_bf16 v[76:79], v[132:135], v[202:205], v[76:79]
	v_mfma_f32_16x16x32_bf16 v[72:75], v[156:159], v[202:205], v[72:75]
	v_mfma_f32_16x16x32_bf16 v[72:75], v[152:155], v[198:201], v[72:75]
	v_mfma_f32_16x16x32_bf16 v[64:67], v[152:155], v[206:209], v[64:67]
	v_mfma_f32_16x16x32_bf16 v[64:67], v[156:159], v[210:213], v[64:67]
	v_mfma_f32_16x16x32_bf16 v[68:71], v[132:135], v[210:213], v[68:71]
	v_mfma_f32_16x16x32_bf16 v[68:71], v[128:131], v[206:209], v[68:71]
	s_setprio 0
	s_setprio 1
	v_mfma_f32_16x16x32_bf16 v[28:31], v[160:163], v[176:179], v[28:31]
	v_mfma_f32_16x16x32_bf16 v[28:31], v[164:167], v[180:183], v[28:31]
	v_mfma_f32_16x16x32_bf16 v[24:27], v[172:175], v[180:183], v[24:27]
	v_mfma_f32_16x16x32_bf16 v[24:27], v[168:171], v[176:179], v[24:27]
	v_mfma_f32_16x16x32_bf16 v[16:19], v[168:171], v[184:187], v[16:19]
	v_mfma_f32_16x16x32_bf16 v[16:19], v[172:175], v[194:197], v[16:19]
	v_mfma_f32_16x16x32_bf16 v[20:23], v[164:167], v[194:197], v[20:23]
	v_mfma_f32_16x16x32_bf16 v[20:23], v[160:163], v[184:187], v[20:23]
	v_mfma_f32_16x16x32_bf16 v[12:15], v[160:163], v[198:201], v[12:15]
	v_mfma_f32_16x16x32_bf16 v[12:15], v[164:167], v[202:205], v[12:15]
	v_mfma_f32_16x16x32_bf16 v[8:11], v[172:175], v[202:205], v[8:11]
	v_mfma_f32_16x16x32_bf16 v[8:11], v[168:171], v[198:201], v[8:11]
	v_mfma_f32_16x16x32_bf16 v[0:3], v[168:171], v[206:209], v[0:3]
	v_mfma_f32_16x16x32_bf16 v[0:3], v[172:175], v[210:213], v[0:3]
	s_setprio 2
	s_barrier
; #define PG8_STAGE(bufoff, gbase, voff) do { _Pragma("unroll") for (int _i = 0; _i < 2; ++_i) \
;         __builtin_amdgcn_global_load_lds((const unsigned*)((const char*)(gbase) + (voff)[_i]), (PG8_LAS unsigned*)(lds + (bufoff) + ldsw + _i * 8192), 16, 0, 0); } while (0)
; #define PG8_LDA(dst, b, h) do { _Pragma("unroll") for (int m = 0; m < 4; ++m) _Pragma("unroll") for (int k = 0; k < 2; ++k) dst[m][k] = *(const PG8_LAS bf16x8*)(lds + PG8_SA(b, h) + aoff + m * 2048 + k * 1024); } while (0)
; #define PG8_WAIT_V(n) asm volatile("s_waitcnt vmcnt(" #n ")" ::: "memory")
; #define PG8_WAIT_L(n) asm volatile("s_waitcnt lgkmcnt(" #n ")" ::: "memory")
; #define PG8_BAR __builtin_amdgcn_s_barrier()
; template <class Epi, class Sched, bool ALIGN_EPI = false, bool SP2 = false>
; __device__ __forceinline__ void gemm_phase(PG8_LAS unsigned char* lds, const Gemm g, const Sched& S, const Epi& E, int tid_in) {
;     ...
;         for (int t = 0; t < nt; t += 2) {
;             const bool last = (t == nt - 2);
;             const char* a1 = cA + (size_t)(t + 1) * kstep;
;             const char* a2 = last ? nA : cA + (size_t)(t + 2) * kstep; const char* b2 = last ? nB : cB + (size_t)(t + 2) * kstep;
;             const char* a3 = a2 + kstep; const char* b3 = b2 + kstep;
;             if (last && has_next) S.a_ready(nxt);
;             if constexpr (SP2) {
;             PG8_LDB(B0, 0, 0); PG8_LDB(B1, 0, 1); PG8_SCHED; PG8_LDA(At, 0, 0); PG8_STAGE(PG8_SA(1, 1), a1 + hstepA, voffA);
;             PG8_WAIT_V(8); PG8_WAIT_L(0); PG8_BAR; PG8_MMA(0, 0, At, B0); PG8_MMA(0, 1, At, B1); PG8_BAR; PG8_SCHED;
;             PG8_LDA(At, 0, 1); PG8_STAGE(PG8_SB(0, 0), b2, voffB); PG8_STAGE(PG8_SB(0, 1), b2 + hstep, voffB); PG8_STAGE(PG8_SA(0, 0), a2, voffA);
;             PG8_WAIT_V(8); PG8_WAIT_L(0); PG8_BAR; PG8_MMA(1, 0, At, B0); PG8_MMA(1, 1, At, B1); PG8_BAR; PG8_SCHED;
;             PG8_LDB(B0, 1, 0); PG8_LDB(B1, 1, 1); PG8_SCHED; PG8_LDA(At, 1, 0); PG8_STAGE(PG8_SA(0, 1), a2 + hstepA, voffA);
;             PG8_WAIT_V(8); PG8_WAIT_L(0); PG8_BAR; PG8_MMA(0, 0, At, B0); PG8_MMA(0, 1, At, B1); PG8_BAR; PG8_SCHED;
;             PG8_LDA(At, 1, 1); PG8_STAGE(PG8_SB(1, 0), b3, voffB); PG8_STAGE(PG8_SB(1, 1), b3 + hstep, voffB); PG8_STAGE(PG8_SA(1, 0), a3, voffA);
;             PG8_WAIT_V(8); PG8_WAIT_L(0); PG8_BAR; PG8_MMA(1, 0, At, B0); PG8_MMA(1, 1, At, B1); PG8_BAR; PG8_SCHED;
	v_mfma_f32_16x16x32_bf16 v[4:7], v[164:167], v[210:213], v[4:7]
	v_mfma_f32_16x16x32_bf16 v[4:7], v[160:163], v[206:209], v[4:7]
	s_setprio 0
	s_add_i32 s54, 0, 0x18000
	s_add_i32 s55, 0, 0x1c000
	v_add_u32_e32 v156, s54, v189
	v_add_u32_e32 v172, s55, v189
	ds_read_b128 v[128:131], v156
	ds_read_b128 v[132:135], v156 offset:1024
	ds_read_b128 v[152:155], v156 offset:2048
	ds_read_b128 v[156:159], v156 offset:3072
	ds_read_b128 v[160:163], v172
	ds_read_b128 v[164:167], v172 offset:1024
	ds_read_b128 v[168:171], v172 offset:2048
	ds_read_b128 v[172:175], v172 offset:3072
	s_add_u32 s20, s26, 0x2b0000
	s_addc_u32 s21, s27, 0
	s_mov_b32 m0, s36
	ds_read_b128 v[176:179], v193 offset:32768
	ds_read_b128 v[180:183], v193 offset:33792
	ds_read_b128 v[184:187], v193 offset:34816
	ds_read_b128 v[194:197], v193 offset:35840
	ds_read_b128 v[198:201], v193 offset:36864
	ds_read_b128 v[202:205], v193 offset:37888
	ds_read_b128 v[206:209], v193 offset:38912
	ds_read_b128 v[210:213], v193 offset:39936
	global_load_lds_dwordx4 v136, s[20:21]
	s_mov_b32 m0, s37
	s_nop 0
	global_load_lds_dwordx4 v140, s[20:21]
	s_waitcnt vmcnt(8)
	s_waitcnt lgkmcnt(0)
	s_barrier
	s_setprio 1
	s_waitcnt lgkmcnt(0)
	v_mfma_f32_16x16x32_bf16 v[124:127], v[128:131], v[176:179], v[124:127]
	v_mfma_f32_16x16x32_bf16 v[124:127], v[132:135], v[180:183], v[124:127]
	v_mfma_f32_16x16x32_bf16 v[120:123], v[156:159], v[180:183], v[120:123]
	v_mfma_f32_16x16x32_bf16 v[120:123], v[152:155], v[176:179], v[120:123]
	v_mfma_f32_16x16x32_bf16 v[112:115], v[152:155], v[184:187], v[112:115]
	v_mfma_f32_16x16x32_bf16 v[112:115], v[156:159], v[194:197], v[112:115]
	v_mfma_f32_16x16x32_bf16 v[116:119], v[132:135], v[194:197], v[116:119]
	v_mfma_f32_16x16x32_bf16 v[116:119], v[128:131], v[184:187], v[116:119]
	v_mfma_f32_16x16x32_bf16 v[108:111], v[128:131], v[198:201], v[108:111]
	v_mfma_f32_16x16x32_bf16 v[108:111], v[132:135], v[202:205], v[108:111]
	v_mfma_f32_16x16x32_bf16 v[104:107], v[156:159], v[202:205], v[104:107]
	v_mfma_f32_16x16x32_bf16 v[104:107], v[152:155], v[198:201], v[104:107]
	v_mfma_f32_16x16x32_bf16 v[96:99], v[152:155], v[206:209], v[96:99]
	v_mfma_f32_16x16x32_bf16 v[96:99], v[156:159], v[210:213], v[96:99]
	v_mfma_f32_16x16x32_bf16 v[100:103], v[132:135], v[210:213], v[100:103]
	v_mfma_f32_16x16x32_bf16 v[100:103], v[128:131], v[206:209], v[100:103]
	s_setprio 0
	s_setprio 1
	v_mfma_f32_16x16x32_bf16 v[60:63], v[160:163], v[176:179], v[60:63]
	v_mfma_f32_16x16x32_bf16 v[60:63], v[164:167], v[180:183], v[60:63]
	v_mfma_f32_16x16x32_bf16 v[56:59], v[172:175], v[180:183], v[56:59]
	v_mfma_f32_16x16x32_bf16 v[56:59], v[168:171], v[176:179], v[56:59]
	v_mfma_f32_16x16x32_bf16 v[48:51], v[168:171], v[184:187], v[48:51]
	v_mfma_f32_16x16x32_bf16 v[48:51], v[172:175], v[194:197], v[48:51]
	v_mfma_f32_16x16x32_bf16 v[52:55], v[164:167], v[194:197], v[52:55]
	v_mfma_f32_16x16x32_bf16 v[52:55], v[160:163], v[184:187], v[52:55]
	v_mfma_f32_16x16x32_bf16 v[44:47], v[160:163], v[198:201], v[44:47]
	v_mfma_f32_16x16x32_bf16 v[44:47], v[164:167], v[202:205], v[44:47]
	v_mfma_f32_16x16x32_bf16 v[40:43], v[172:175], v[202:205], v[40:43]
	v_mfma_f32_16x16x32_bf16 v[40:43], v[168:171], v[198:201], v[40:43]
	v_mfma_f32_16x16x32_bf16 v[32:35], v[168:171], v[206:209], v[32:35]
	v_mfma_f32_16x16x32_bf16 v[32:35], v[172:175], v[210:213], v[32:35]
	s_setprio 2
	s_barrier
	v_mfma_f32_16x16x32_bf16 v[36:39], v[164:167], v[210:213], v[36:39]
	v_mfma_f32_16x16x32_bf16 v[36:39], v[160:163], v[206:209], v[36:39]
	s_setprio 0
	s_add_i32 s20, s54, s33
	s_mov_b32 m0, s20
	ds_read_b128 v[176:179], v193 offset:49152
	ds_read_b128 v[180:183], v193 offset:50176
	ds_read_b128 v[184:187], v193 offset:51200
	ds_read_b128 v[194:197], v193 offset:52224
	ds_read_b128 v[198:201], v193 offset:53248
	ds_read_b128 v[202:205], v193 offset:54272
	ds_read_b128 v[206:209], v193 offset:55296
	ds_read_b128 v[210:213], v193 offset:56320
	global_load_lds_dwordx4 v138, s[98:99]
	s_add_i32 m0, s20, 0x2000
	s_add_u32 s20, s24, 0x2b0080
	s_addc_u32 s21, s25, 0
	s_add_i32 s24, s55, s33
	global_load_lds_dwordx4 v142, s[98:99]
	s_mov_b32 m0, s24
	s_nop 0
	global_load_lds_dwordx4 v138, s[20:21]
	s_add_i32 m0, s24, 0x2000
	s_nop 0
	global_load_lds_dwordx4 v142, s[20:21]
	s_mov_b32 m0, s42
	s_nop 0
	global_load_lds_dwordx4 v136, s[100:101]
	s_mov_b32 m0, s43
	s_nop 0
	global_load_lds_dwordx4 v140, s[100:101]
	s_waitcnt vmcnt(8)
	s_waitcnt lgkmcnt(0)
	s_barrier
	s_setprio 1
	s_waitcnt lgkmcnt(0)
	v_mfma_f32_16x16x32_bf16 v[92:95], v[128:131], v[176:179], v[92:95]
	v_mfma_f32_16x16x32_bf16 v[92:95], v[132:135], v[180:183], v[92:95]
	v_mfma_f32_16x16x32_bf16 v[88:91], v[156:159], v[180:183], v[88:91]
	v_mfma_f32_16x16x32_bf16 v[88:91], v[152:155], v[176:179], v[88:91]
	v_mfma_f32_16x16x32_bf16 v[80:83], v[152:155], v[184:187], v[80:83]
	v_mfma_f32_16x16x32_bf16 v[80:83], v[156:159], v[194:197], v[80:83]
	v_mfma_f32_16x16x32_bf16 v[84:87], v[132:135], v[194:197], v[84:87]
	v_mfma_f32_16x16x32_bf16 v[84:87], v[128:131], v[184:187], v[84:87]
	v_mfma_f32_16x16x32_bf16 v[76:79], v[128:131], v[198:201], v[76:79]
	v_mfma_f32_16x16x32_bf16 v[76:79], v[132:135], v[202:205], v[76:79]
	v_mfma_f32_16x16x32_bf16 v[72:75], v[156:159], v[202:205], v[72:75]
	v_mfma_f32_16x16x32_bf16 v[72:75], v[152:155], v[198:201], v[72:75]
	v_mfma_f32_16x16x32_bf16 v[64:67], v[152:155], v[206:209], v[64:67]
	v_mfma_f32_16x16x32_bf16 v[64:67], v[156:159], v[210:213], v[64:67]
	v_mfma_f32_16x16x32_bf16 v[68:71], v[132:135], v[210:213], v[68:71]
	v_mfma_f32_16x16x32_bf16 v[68:71], v[128:131], v[206:209], v[68:71]
	s_setprio 0
	s_setprio 1
	v_mfma_f32_16x16x32_bf16 v[28:31], v[160:163], v[176:179], v[28:31]
	v_mfma_f32_16x16x32_bf16 v[28:31], v[164:167], v[180:183], v[28:31]
	v_mfma_f32_16x16x32_bf16 v[24:27], v[172:175], v[180:183], v[24:27]
	v_mfma_f32_16x16x32_bf16 v[24:27], v[168:171], v[176:179], v[24:27]
	v_mfma_f32_16x16x32_bf16 v[16:19], v[168:171], v[184:187], v[16:19]
	v_mfma_f32_16x16x32_bf16 v[16:19], v[172:175], v[194:197], v[16:19]
	v_mfma_f32_16x16x32_bf16 v[20:23], v[164:167], v[194:197], v[20:23]
	v_mfma_f32_16x16x32_bf16 v[20:23], v[160:163], v[184:187], v[20:23]
	v_mfma_f32_16x16x32_bf16 v[12:15], v[160:163], v[198:201], v[12:15]
	v_mfma_f32_16x16x32_bf16 v[12:15], v[164:167], v[202:205], v[12:15]
	v_mfma_f32_16x16x32_bf16 v[8:11], v[172:175], v[202:205], v[8:11]
	v_mfma_f32_16x16x32_bf16 v[8:11], v[168:171], v[198:201], v[8:11]
	v_mfma_f32_16x16x32_bf16 v[0:3], v[168:171], v[206:209], v[0:3]
	v_mfma_f32_16x16x32_bf16 v[0:3], v[172:175], v[210:213], v[0:3]
	s_setprio 2
	s_barrier
	v_mfma_f32_16x16x32_bf16 v[4:7], v[164:167], v[210:213], v[4:7]
	v_mfma_f32_16x16x32_bf16 v[4:7], v[160:163], v[206:209], v[4:7]
	s_setprio 0
	s_add_i32 s53, s53, 2
	s_add_u32 s51, s51, 0x100
	s_addc_u32 s52, s52, 0
	s_cmpk_gt_u32 s53, 0xa9
	s_mov_b64 s[20:21], s[22:23]
	s_cbranch_scc0 .LBB0_1328
	s_and_b64 vcc, exec, s[14:15]
	s_cbranch_vccz .LBB0_1331
	s_barrier
